# row passes: norm gains hoisted out of the row loop (one wait per row); rwkv prep prologue: weight pairs loaded 16 pairs per wait; plus pool load fix and scanner
# speedup vs baseline: 1.0361x; 1.0361x over previous
; __device__ __forceinline__ unsigned pk2(float lo, float hi) { f32x2_t v = {lo, hi}; bf16x2_t b = __builtin_convertvector(v, bf16x2_t); return __builtin_bit_cast(unsigned, b); }
; __device__ __forceinline__ void norm_row_to_bf16(const float* xrow, const float* g, bf16* hrow, int lane) {
;     f32x4 v[4]; float s = 0.f;
; #pragma unroll
;     for (int j = 0; j < 4; ++j) { v[j] = *((const f32x4*)xrow + lane + 64 * j); s += (v[j].x * v[j].x + v[j].y * v[j].y) + (v[j].z * v[j].z + v[j].w * v[j].w); }
;     const float rstd = rsqrtf(wave_sum(s) * (1.f / D) + RMS_EPS);
; #pragma unroll
;     for (int j = 0; j < 4; ++j) { const f32x4 gg = *((const f32x4*)g + lane + 64 * j); u32x2 o; o.x = pk2(v[j].x * rstd * gg.x, v[j].y * rstd * gg.y); o.y = pk2(v[j].z * rstd * gg.z, v[j].w * rstd * gg.w);
;         *((u32x2*)hrow + lane + 64 * j) = o; }
; }
; __device__ __forceinline__ void phase_pre(const Args& a, unsigned char* lds) {
;     ...
;     bf16* H = (bf16*)(ws_l + WS_H);
;     for (int m = gw; m < MR; m += NGW) {
;         const float* xr = m < MP ? in_I_XP + (size_t)m * D : in_I_XS + (size_t)(m - MP) * D;
;         norm_row_to_bf16(xr, in_I_NG, H + (size_t)m * D, lane);
;     }
.LBB0_52:
	s_or_b64 exec, exec, s[6:7]
	s_mov_b32 s0, 0x8080
	v_cmp_gt_i32_e32 vcc, s0, v2
	s_and_saveexec_b64 s[6:7], vcc
	s_cbranch_execz .LBB0_57
	v_mov_b32_e32 v9, 0
	v_mov_b32_e32 v7, v9
	v_ashrrev_i32_e32 v3, 31, v2
	v_lshlrev_b32_e32 v8, 4, v4
	v_lshl_add_u64 v[6:7], s[22:23], 0, v[6:7]
	s_mov_b64 s[0:1], 0x5100000
	s_ashr_i32 s61, s60, 31
	v_lshlrev_b64 v[12:13], 12, v[2:3]
	v_lshl_add_u64 v[10:11], s[4:5], 0, v[8:9]
	v_lshl_add_u64 v[6:7], v[6:7], 0, s[0:1]
	v_lshl_add_u64 v[12:13], s[12:13], 0, v[12:13]
	s_lshl_b64 s[4:5], s[60:61], 12
	s_mov_b64 s[8:9], 0
	s_movk_i32 s0, 0x7fff
	v_lshlrev_b32_e32 v4, 4, v4
	v_mov_b32_e32 v5, v9
	v_mov_b32_e32 v1, 0x358637bd
	s_mov_b32 s1, 0x800000
	s_mov_b32 s3, 0x807f
	global_load_dwordx4 v[204:207], v[10:11], off offset:1024
	global_load_dwordx4 v[208:211], v[10:11], off offset:2048
	global_load_dwordx4 v[212:215], v[10:11], off offset:3072
	s_waitcnt vmcnt(0)
	s_branch .LBB0_55
.LBB0_54:
	s_or_b64 exec, exec, s[10:11]
	v_lshl_add_u64 v[36:37], v[16:17], 0, v[4:5]
	global_load_dwordx4 v[16:19], v[36:37], off
	global_load_dwordx4 v[20:23], v[36:37], off offset:1024
	global_load_dwordx4 v[24:27], v[36:37], off offset:3072
	global_load_dwordx4 v[28:31], v[36:37], off offset:2048
	global_load_dwordx4 v[32:35], v[10:11], off
	v_lshlrev_b64 v[14:15], 11, v[14:15]
	v_lshl_add_u64 v[2:3], v[2:3], 0, s[60:61]
	v_lshl_add_u64 v[12:13], v[12:13], 0, s[4:5]
	s_waitcnt vmcnt(4)
	v_pk_mul_f32 v[36:37], v[18:19], v[18:19]
	v_pk_mul_f32 v[38:39], v[16:17], v[16:17]
	s_waitcnt vmcnt(3)
	v_pk_mul_f32 v[40:41], v[22:23], v[22:23]
	v_pk_mul_f32 v[42:43], v[20:21], v[20:21]
	v_pk_mov_b32 v[46:47], v[38:39], v[36:37] op_sel:[1,0]
	v_mov_b32_e32 v39, v37
	v_pk_mov_b32 v[36:37], v[42:43], v[40:41] op_sel:[1,0]
	v_mov_b32_e32 v43, v41
	s_waitcnt vmcnt(1)
	v_mul_f32_e32 v8, v29, v29
	v_mul_f32_e32 v44, v31, v31
	v_pk_add_f32 v[38:39], v[46:47], v[38:39]
	v_pk_add_f32 v[36:37], v[36:37], v[42:43]
	v_mul_f32_e32 v48, v24, v24
	v_mul_f32_e32 v49, v25, v25
	v_mul_f32_e32 v50, v26, v26
	v_mul_f32_e32 v51, v27, v27
	v_pk_fma_f32 v[40:41], v[28:29], v[28:29], v[8:9] op_sel_hi:[1,1,0]
	v_pk_fma_f32 v[44:45], v[30:31], v[30:31], v[44:45] op_sel_hi:[1,1,0]
	v_pk_add_f32 v[38:39], v[38:39], v[38:39] op_sel:[0,1] op_sel_hi:[1,0]
	v_pk_add_f32 v[36:37], v[36:37], v[36:37] op_sel:[0,1] op_sel_hi:[1,0]
	v_mov_b32_e32 v41, v50
	v_mov_b32_e32 v45, v51
	v_mov_b32_e32 v39, v48
	v_mov_b32_e32 v37, v49
	v_pk_add_f32 v[40:41], v[40:41], v[44:45]
	v_pk_add_f32 v[36:37], v[38:39], v[36:37]
	s_nop 0
	v_pk_add_f32 v[36:37], v[36:37], v[40:41]
	s_nop 0
	v_add_f32_e32 v8, v36, v37
	s_nop 1
	v_add_f32_dpp v8, v8, v8 quad_perm:[1,0,3,2] row_mask:0xf bank_mask:0xf bound_ctrl:1
	s_nop 1
	v_add_f32_dpp v8, v8, v8 quad_perm:[2,3,0,1] row_mask:0xf bank_mask:0xf bound_ctrl:1
	s_nop 1
	v_add_f32_dpp v8, v8, v8 row_half_mirror row_mask:0xf bank_mask:0xf bound_ctrl:1
	s_nop 1
	v_add_f32_dpp v8, v8, v8 row_mirror row_mask:0xf bank_mask:0xf bound_ctrl:1
	s_nop 0
	v_readlane_b32 s12, v8, 16
	v_readlane_b32 s13, v8, 48
	v_readlane_b32 s10, v8, 0
	v_readlane_b32 s11, v8, 32
	v_mov_b32_e32 v36, s12
	v_mov_b32_e32 v37, s13
	v_pk_add_f32 v[36:37], s[10:11], v[36:37]
	s_nop 0
	v_add_f32_e32 v8, v36, v37
	v_fmamk_f32 v8, v8, 0x3a800000, v1
	v_mul_f32_e32 v36, 0x4b800000, v8
	v_cmp_gt_f32_e32 vcc, s1, v8
	s_nop 1
	v_cndmask_b32_e32 v8, v8, v36, vcc
	v_rsq_f32_e32 v8, v8
	v_lshl_add_u64 v[36:37], v[6:7], 0, v[14:15]
	v_mul_f32_e32 v14, 0x45800000, v8
	v_cndmask_b32_e32 v8, v8, v14, vcc
	v_pk_mul_f32 v[14:15], v[16:17], v[8:9] op_sel_hi:[1,0]
	v_pk_mul_f32 v[16:17], v[18:19], v[8:9] op_sel_hi:[1,0]
	s_waitcnt vmcnt(0)
	v_pk_mul_f32 v[14:15], v[32:33], v[14:15]
	v_pk_mul_f32 v[16:17], v[34:35], v[16:17]
	v_cvt_pk_bf16_f32 v14, v14, v15
	v_cvt_pk_bf16_f32 v15, v16, v17
	global_store_dwordx2 v[36:37], v[14:15], off
	v_pk_mul_f32 v[18:19], v[20:21], v[8:9] op_sel_hi:[1,0]
	v_pk_mul_f32 v[20:21], v[22:23], v[8:9] op_sel_hi:[1,0]
	v_cmp_lt_i32_e32 vcc, s3, v2
	s_or_b64 s[8:9], vcc, s[8:9]
	v_pk_mul_f32 v[14:15], v[204:205], v[18:19]
	v_pk_mul_f32 v[16:17], v[206:207], v[20:21]
	v_cvt_pk_bf16_f32 v14, v14, v15
	v_cvt_pk_bf16_f32 v15, v16, v17
	global_store_dwordx2 v[36:37], v[14:15], off offset:512
	v_pk_mul_f32 v[18:19], v[28:29], v[8:9] op_sel_hi:[1,0]
	v_pk_mul_f32 v[20:21], v[30:31], v[8:9] op_sel_hi:[1,0]
	v_pk_mul_f32 v[14:15], v[208:209], v[18:19]
	v_pk_mul_f32 v[16:17], v[210:211], v[20:21]
	v_cvt_pk_bf16_f32 v14, v14, v15
	v_cvt_pk_bf16_f32 v15, v16, v17
	global_store_dwordx2 v[36:37], v[14:15], off offset:1024
	v_pk_mul_f32 v[18:19], v[24:25], v[8:9] op_sel_hi:[1,0]
	v_pk_mul_f32 v[20:21], v[26:27], v[8:9] op_sel_hi:[1,0]
	v_pk_mul_f32 v[14:15], v[212:213], v[18:19]
	v_pk_mul_f32 v[16:17], v[214:215], v[20:21]
	v_cvt_pk_bf16_f32 v14, v14, v15
	v_cvt_pk_bf16_f32 v15, v16, v17
	global_store_dwordx2 v[36:37], v[14:15], off offset:1536
	s_andn2_b64 exec, exec, s[8:9]
	s_cbranch_execz .LBB0_57

; __device__ __forceinline__ int ltid() { int t = threadIdx.x; asm volatile("" : "+v"(t)); return t; }
; template <bool SRC_F32, bool DST_F32, bool HAS_H>
; __device__ __forceinline__ void phase_rowpass(const void* xp, const void* xs, const bf16* Y, float coef, const float* gpost, const float* gpre, void* xdst, bf16* H) {
;     const int tid = ltid(), lane = tid & 63, wave = tid >> 6;
;     const int gw = blockIdx.x * NWAVES + wave, NGW = gridDim.x * NWAVES;
;     f32x4 y[4], x[4], nxf[4]; u32x2 ny[4], nxb[4];
;     ...
;     if (gw < MR) RP_LOAD(gw);
;     for (int m = gw; m < MR; m += NGW) {
; #pragma unroll
;         for (int j = 0; j < 4; ++j) { y[j] = (f32x4){bflo(ny[j].x), bfhi(ny[j].x), bflo(ny[j].y), bfhi(ny[j].y)};
;             x[j] = SRC_F32 ? nxf[j] : (f32x4){bflo(nxb[j].x), bfhi(nxb[j].x), bflo(nxb[j].y), bfhi(nxb[j].y)}; }
;         if (m + NGW < MR) RP_LOAD(m + NGW);
;         float s = 0.f;
; #pragma unroll
;         for (int j = 0; j < 4; ++j) s += (y[j].x * y[j].x + y[j].y * y[j].y) + (y[j].z * y[j].z + y[j].w * y[j].w);
;         const float rstd = rsqrtf(wave_sum(s) * (1.f / D) + RMS_EPS) * coef;
;         float s2 = 0.f;
; #pragma unroll
;         for (int j = 0; j < 4; ++j) { const f32x4 gg = *((const f32x4*)gpost + lane + 64 * j);
;             x[j].x += y[j].x * rstd * gg.x; x[j].y += y[j].y * rstd * gg.y; x[j].z += y[j].z * rstd * gg.z; x[j].w += y[j].w * rstd * gg.w;
.LBB0_229:
	s_or_b64 exec, exec, s[4:5]
	v_readlane_b32 s6, v253, 2
	v_readlane_b32 s7, v253, 3
	s_waitcnt lgkmcnt(0)
	s_barrier
	s_load_dwordx4 s[12:15], s[6:7], 0xe0
	s_load_dwordx2 s[4:5], s[6:7], 0x40
	s_mul_i32 s78, s44, 0x1800
	v_readlane_b32 s16, v254, 58
	v_readlane_b32 s17, v254, 59
	s_waitcnt lgkmcnt(0)
	s_add_u32 s8, s14, 0x142e0000
	s_addc_u32 s9, s15, 0
	s_lshl_b64 s[10:11], s[78:79], 2
	s_add_u32 s4, s4, s10
	v_writelane_b32 v255, s10, 2
	s_addc_u32 s5, s5, s11
	s_and_b64 vcc, exec, s[16:17]
	v_writelane_b32 v255, s11, 3
	s_mov_b64 s[10:11], -1
	s_cbranch_vccz .LBB0_236
	v_mov_b32_e32 v0, v172
	v_readlane_b32 s0, v253, 6
	v_ashrrev_i32_e32 v8, 6, v0
	s_nop 0
	v_add_u32_e32 v4, s0, v8
	v_cmp_gt_i32_e32 vcc, s93, v4
	s_and_saveexec_b64 s[16:17], vcc
	s_cbranch_execz .LBB0_235
	v_ashrrev_i32_e32 v5, 31, v4
	v_and_b32_e32 v14, 63, v0
	v_lshlrev_b64 v[10:11], 11, v[4:5]
	v_lshl_add_u64 v[0:1], s[8:9], 0, v[10:11]
	v_lshlrev_b32_e32 v140, 3, v14
	v_lshl_add_u64 v[6:7], s[12:13], 0, v[10:11]
	v_lshl_add_u64 v[2:3], v[0:1], 0, v[140:141]
	v_lshl_add_u64 v[12:13], v[6:7], 0, v[140:141]
	global_load_dwordx2 v[40:41], v[2:3], off
	global_load_dwordx2 v[36:37], v[2:3], off offset:512
	global_load_dwordx2 v[0:1], v[2:3], off offset:1536
	global_load_dwordx2 v[34:35], v[2:3], off offset:1024
	s_nop 0
	global_load_dwordx2 v[2:3], v[12:13], off offset:1536
	global_load_dwordx2 v[38:39], v[12:13], off offset:1024
	global_load_dwordx2 v[42:43], v[12:13], off offset:512
	global_load_dwordx2 v[44:45], v[12:13], off
	v_readlane_b32 s0, v254, 21
	v_mov_b32_e32 v9, v141
	s_mov_b64 s[10:11], 0x1000
	v_add_u32_e32 v12, s0, v8
	v_lshlrev_b32_e32 v8, 4, v14
	v_ashrrev_i32_e32 v13, 31, v12
	v_lshl_add_u64 v[14:15], s[4:5], 0, v[8:9]
	v_lshl_add_u64 v[8:9], s[14:15], 0, v[10:11]
	v_lshlrev_b64 v[16:17], 11, v[12:13]
	v_lshl_add_u64 v[10:11], v[14:15], 0, s[10:11]
	s_mov_b64 s[10:11], 0x2000
	s_mov_b64 s[18:19], 0
	v_lshl_add_u64 v[12:13], v[14:15], 0, s[10:11]
	v_lshl_add_u64 v[14:15], s[14:15], 0, v[16:17]
	v_lshl_add_u64 v[16:17], s[12:13], 0, v[16:17]
	s_waitcnt vmcnt(7)
	v_mov_b64_e32 v[24:25], v[40:41]
	s_waitcnt vmcnt(6)
	v_mov_b64_e32 v[22:23], v[36:37]
	s_waitcnt vmcnt(5)
	v_mov_b64_e32 v[18:19], v[0:1]
	s_waitcnt vmcnt(4)
	v_mov_b64_e32 v[20:21], v[34:35]
	s_waitcnt vmcnt(3)
	v_mov_b64_e32 v[26:27], v[2:3]
	s_waitcnt vmcnt(2)
	v_mov_b64_e32 v[28:29], v[38:39]
	s_waitcnt vmcnt(1)
	v_mov_b64_e32 v[30:31], v[42:43]
	s_waitcnt vmcnt(0)
	v_mov_b64_e32 v[32:33], v[44:45]
	global_load_dwordx4 v[200:203], v[10:11], off
	global_load_dwordx4 v[204:207], v[10:11], off offset:1024
	global_load_dwordx4 v[208:211], v[10:11], off offset:2048
	global_load_dwordx4 v[212:215], v[10:11], off offset:3072
	global_load_dwordx4 v[216:219], v[12:13], off
	global_load_dwordx4 v[220:223], v[12:13], off offset:1024
	global_load_dwordx4 v[224:227], v[12:13], off offset:2048
	global_load_dwordx4 v[228:231], v[12:13], off offset:3072
	s_waitcnt vmcnt(0)
	s_branch .LBB0_233
.LBB0_232:
	s_or_b64 exec, exec, s[10:11]
	v_and_b32_e32 v67, 0xffff0000, v40
	v_and_b32_e32 v65, 0xffff0000, v41
	v_lshlrev_b32_e32 v66, 16, v40
	v_lshlrev_b32_e32 v64, 16, v41
	v_lshlrev_b32_e32 v59, 16, v37
	v_lshlrev_b32_e32 v58, 16, v36
	v_and_b32_e32 v57, 0xffff0000, v37
	v_and_b32_e32 v56, 0xffff0000, v36
	v_lshlrev_b32_e32 v60, 16, v42
	v_and_b32_e32 v61, 0xffff0000, v42
	v_lshlrev_b32_e32 v54, 16, v43
	v_and_b32_e32 v55, 0xffff0000, v43
	v_lshlrev_b32_e32 v42, 16, v2
	v_and_b32_e32 v43, 0xffff0000, v2
	v_lshlrev_b32_e32 v36, 16, v3
	v_and_b32_e32 v37, 0xffff0000, v3
	v_mov_b32_e32 v2, v67
	v_mov_b32_e32 v3, v65
	v_lshlrev_b32_e32 v68, 16, v44
	v_and_b32_e32 v69, 0xffff0000, v44
	v_lshlrev_b32_e32 v62, 16, v45
	v_and_b32_e32 v63, 0xffff0000, v45
	v_lshlrev_b32_e32 v52, 16, v38
	v_and_b32_e32 v53, 0xffff0000, v38
	v_lshlrev_b32_e32 v44, 16, v39
	v_and_b32_e32 v45, 0xffff0000, v39
	v_lshlrev_b32_e32 v40, 16, v0
	v_and_b32_e32 v41, 0xffff0000, v0
	v_lshlrev_b32_e32 v38, 16, v1
	v_and_b32_e32 v39, 0xffff0000, v1
	v_mov_b32_e32 v0, v66
	v_mov_b32_e32 v1, v64
	v_pk_mul_f32 v[2:3], v[2:3], v[2:3]
	v_lshlrev_b32_e32 v46, 16, v35
	v_pk_fma_f32 v[0:1], v[0:1], v[0:1], v[2:3]
	v_and_b32_e32 v47, 0xffff0000, v35
	v_pk_add_f32 v[0:1], v[0:1], v[0:1] op_sel_hi:[0,1]
	v_lshlrev_b32_e32 v50, 16, v34
	v_pk_mul_f32 v[2:3], v[56:57], v[56:57]
	v_mul_f32_e32 v0, v46, v46
	v_and_b32_e32 v51, 0xffff0000, v34
	v_pk_fma_f32 v[2:3], v[58:59], v[58:59], v[2:3]
	v_pk_fma_f32 v[34:35], v[46:47], v[46:47], v[0:1] op_sel_hi:[1,1,0]
	v_mul_f32_e32 v0, v50, v50
	v_pk_add_f32 v[2:3], v[2:3], v[2:3] op_sel_hi:[0,1]
	v_pk_mul_f32 v[48:49], v[40:41], v[40:41]
	v_pk_mul_f32 v[70:71], v[38:39], v[38:39]
	v_pk_fma_f32 v[72:73], v[50:51], v[50:51], v[0:1] op_sel_hi:[1,1,0]
	v_mov_b32_e32 v34, v49
	v_mov_b32_e32 v72, v48
	v_mov_b32_e32 v2, v70
	v_mov_b32_e32 v0, v71
	v_pk_add_f32 v[34:35], v[72:73], v[34:35]
	v_pk_add_f32 v[0:1], v[2:3], v[0:1]
	s_mov_b32 s0, 0x5100000
	v_pk_add_f32 v[0:1], v[34:35], v[0:1]
	v_lshl_add_u64 v[34:35], v[6:7], 0, v[140:141]
	v_add_f32_e32 v0, v0, v1
	v_lshl_add_u64 v[6:7], v[6:7], 0, s[82:83]
	v_lshl_add_u64 v[14:15], v[14:15], 0, s[82:83]
	v_add_f32_dpp v0, v0, v0 quad_perm:[1,0,3,2] row_mask:0xf bank_mask:0xf bound_ctrl:1
	v_lshl_add_u64 v[16:17], v[16:17], 0, s[82:83]
	s_nop 0
	v_add_f32_dpp v0, v0, v0 quad_perm:[2,3,0,1] row_mask:0xf bank_mask:0xf bound_ctrl:1
	s_nop 1
	v_add_f32_dpp v0, v0, v0 row_half_mirror row_mask:0xf bank_mask:0xf bound_ctrl:1
	s_nop 1
	v_add_f32_dpp v0, v0, v0 row_mirror row_mask:0xf bank_mask:0xf bound_ctrl:1
	s_nop 0
	v_readlane_b32 s20, v0, 16
	v_readlane_b32 s21, v0, 48
	v_readlane_b32 s10, v0, 0
	v_readlane_b32 s11, v0, 32
	v_mov_b32_e32 v0, s20
	v_mov_b32_e32 v1, s21
	v_pk_add_f32 v[0:1], s[10:11], v[0:1]
	s_nop 0
	v_add_f32_e32 v0, v0, v1
	v_fmamk_f32 v0, v0, 0x3a800000, v177
	v_cmp_gt_f32_e32 vcc, s65, v0
	v_mul_f32_e32 v1, 0x4b800000, v0
	s_nop 0
	v_cndmask_b32_e32 v0, v0, v1, vcc
	v_rsq_f32_e32 v0, v0
	s_nop 0
	v_mul_f32_e32 v1, 0x45800000, v0
	v_cndmask_b32_e32 v0, v0, v1, vcc
	v_mul_f32_e32 v48, 0.5, v0
	v_pk_mul_f32 v[66:67], v[48:49], v[66:67] op_sel_hi:[0,1]
	v_pk_mul_f32 v[50:51], v[48:49], v[50:51] op_sel_hi:[0,1]
	v_pk_mul_f32 v[46:47], v[48:49], v[46:47] op_sel_hi:[0,1]
	v_pk_mul_f32 v[40:41], v[48:49], v[40:41] op_sel_hi:[0,1]
	v_pk_mul_f32 v[38:39], v[48:49], v[38:39] op_sel_hi:[0,1]
	s_waitcnt vmcnt(0)
; __device__ __forceinline__ unsigned pk2(float lo, float hi) { f32x2_t v = {lo, hi}; bf16x2_t b = __builtin_convertvector(v, bf16x2_t); return __builtin_bit_cast(unsigned, b); }
; template <bool SRC_F32, bool DST_F32, bool HAS_H>
; __device__ __forceinline__ void phase_rowpass(const void* xp, const void* xs, const bf16* Y, float coef, const float* gpost, const float* gpre, void* xdst, bf16* H) {
;     ...
;         for (int j = 0; j < 4; ++j) { const f32x4 gg = *((const f32x4*)gpost + lane + 64 * j);
;             x[j].x += y[j].x * rstd * gg.x; x[j].y += y[j].y * rstd * gg.y; x[j].z += y[j].z * rstd * gg.z; x[j].w += y[j].w * rstd * gg.w;
;             s2 += (x[j].x * x[j].x + x[j].y * x[j].y) + (x[j].z * x[j].z + x[j].w * x[j].w);
;             if (DST_F32) *((f32x4*)((float*)xdst + (size_t)m * D) + lane + 64 * j) = x[j];
;             else { u32x2 o; o.x = pk2(x[j].x, x[j].y); o.y = pk2(x[j].z, x[j].w); *((u32x2*)((bf16*)xdst + (size_t)m * D) + lane + 64 * j) = o; } }
;         if (HAS_H) {
;             const float r2 = rsqrtf(wave_sum(s2) * (1.f / D) + RMS_EPS);
; #pragma unroll
;             for (int j = 0; j < 4; ++j) { const f32x4 gg = *((const f32x4*)gpre + lane + 64 * j); u32x2 o; o.x = pk2(x[j].x * r2 * gg.x, x[j].y * r2 * gg.y); o.y = pk2(x[j].z * r2 * gg.z, x[j].w * r2 * gg.w);
;                 *((u32x2*)(H + (size_t)m * D) + lane + 64 * j) = o; }
	v_pk_fma_f32 v[66:67], v[200:201], v[66:67], v[68:69]
	v_pk_mul_f32 v[0:1], v[48:49], v[64:65] op_sel_hi:[0,1]
	v_pk_fma_f32 v[62:63], v[202:203], v[0:1], v[62:63]
	v_mov_b32_e32 v2, v67
	v_mov_b32_e32 v3, v63
	v_mov_b32_e32 v0, v66
	v_mov_b32_e32 v1, v62
	v_pk_mul_f32 v[2:3], v[2:3], v[2:3]
	v_mov_b32_e32 v68, v58
	v_pk_fma_f32 v[0:1], v[0:1], v[0:1], v[2:3]
	v_mov_b32_e32 v69, v56
	v_pk_add_f32 v[64:65], v[0:1], v[0:1] op_sel_hi:[0,1]
	v_cvt_pk_bf16_f32 v0, v66, v67
	v_cvt_pk_bf16_f32 v1, v62, v63
	global_store_dwordx2 v[34:35], v[0:1], off
	v_mov_b32_e32 v56, v59
	v_pk_mul_f32 v[68:69], v[48:49], v[68:69] op_sel_hi:[0,1]
	v_pk_mul_f32 v[56:57], v[48:49], v[56:57] op_sel_hi:[0,1]
	v_pk_fma_f32 v[0:1], v[204:205], v[68:69], v[60:61]
	v_pk_fma_f32 v[2:3], v[206:207], v[56:57], v[54:55]
	v_mov_b32_e32 v56, v1
	v_mov_b32_e32 v57, v3
	v_mov_b32_e32 v54, v0
	v_mov_b32_e32 v55, v2
	v_pk_mul_f32 v[56:57], v[56:57], v[56:57]
	s_nop 0
	v_pk_fma_f32 v[54:55], v[54:55], v[54:55], v[56:57]
	s_nop 0
	v_pk_add_f32 v[58:59], v[54:55], v[54:55] op_sel_hi:[0,1]
	v_cvt_pk_bf16_f32 v54, v0, v1
	v_cvt_pk_bf16_f32 v55, v2, v3
	global_store_dwordx2 v[34:35], v[54:55], off offset:512
	v_pk_fma_f32 v[50:51], v[208:209], v[50:51], v[52:53]
	v_pk_fma_f32 v[44:45], v[210:211], v[46:47], v[44:45]
	v_cvt_pk_bf16_f32 v52, v50, v51
	v_cvt_pk_bf16_f32 v53, v44, v45
	global_store_dwordx2 v[34:35], v[52:53], off offset:1024
	v_mul_f32_e32 v46, v50, v50
	v_pk_fma_f32 v[46:47], v[50:51], v[50:51], v[46:47] op_sel_hi:[1,1,0]
	v_pk_fma_f32 v[40:41], v[212:213], v[40:41], v[42:43]
	v_mul_f32_e32 v46, v44, v44
	v_pk_fma_f32 v[36:37], v[214:215], v[38:39], v[36:37]
	v_pk_fma_f32 v[56:57], v[44:45], v[44:45], v[46:47] op_sel_hi:[1,1,0]
	v_pk_mul_f32 v[38:39], v[40:41], v[40:41]
	v_pk_mul_f32 v[42:43], v[36:37], v[36:37]
	v_mov_b32_e32 v46, v38
	v_mov_b32_e32 v56, v39
	v_mov_b32_e32 v64, v42
	v_mov_b32_e32 v58, v43
	v_pk_add_f32 v[38:39], v[46:47], v[56:57]
	v_pk_add_f32 v[42:43], v[64:65], v[58:59]
	s_nop 0
	v_pk_add_f32 v[38:39], v[38:39], v[42:43]
	s_nop 0
	v_add_f32_e32 v5, v38, v39
	v_cvt_pk_bf16_f32 v38, v40, v41
	v_cvt_pk_bf16_f32 v39, v36, v37
	global_store_dwordx2 v[34:35], v[38:39], off offset:1536
	v_add_f32_dpp v5, v5, v5 quad_perm:[1,0,3,2] row_mask:0xf bank_mask:0xf bound_ctrl:1
	v_lshl_add_u64 v[38:39], v[8:9], 0, v[140:141]
	v_lshl_add_u64 v[8:9], v[8:9], 0, s[82:83]
	v_add_f32_dpp v5, v5, v5 quad_perm:[2,3,0,1] row_mask:0xf bank_mask:0xf bound_ctrl:1
	s_nop 1
	v_add_f32_dpp v5, v5, v5 row_half_mirror row_mask:0xf bank_mask:0xf bound_ctrl:1
	s_nop 1
	v_add_f32_dpp v5, v5, v5 row_mirror row_mask:0xf bank_mask:0xf bound_ctrl:1
	s_nop 0
	v_readlane_b32 s20, v5, 16
	v_readlane_b32 s21, v5, 48
	v_readlane_b32 s10, v5, 0
	v_readlane_b32 s11, v5, 32
	v_mov_b32_e32 v34, s20
	v_mov_b32_e32 v35, s21
	v_pk_add_f32 v[34:35], s[10:11], v[34:35]
	s_nop 0
	v_add_f32_e32 v5, v34, v35
	v_fmamk_f32 v5, v5, 0x3a800000, v177
	v_cmp_gt_f32_e32 vcc, s65, v5
	v_mul_f32_e32 v34, 0x4b800000, v5
	s_nop 0
	v_cndmask_b32_e32 v5, v5, v34, vcc
	v_rsq_f32_e32 v5, v5
	s_nop 0
	v_mul_f32_e32 v34, 0x45800000, v5
	v_cndmask_b32_e32 v34, v5, v34, vcc
	v_pk_mul_f32 v[42:43], v[66:67], v[34:35] op_sel_hi:[1,0]
	v_add_co_u32_e32 v38, vcc, s0, v38
	v_pk_mul_f32 v[0:1], v[0:1], v[34:35] op_sel_hi:[1,0]
	s_nop 0
	v_addc_co_u32_e32 v39, vcc, 0, v39, vcc
	v_pk_mul_f32 v[2:3], v[2:3], v[34:35] op_sel_hi:[1,0]
	v_pk_mul_f32 v[40:41], v[40:41], v[34:35] op_sel_hi:[1,0]
	v_pk_mul_f32 v[42:43], v[216:217], v[42:43]
	v_pk_mul_f32 v[46:47], v[62:63], v[34:35] op_sel_hi:[1,0]
	v_cvt_pk_bf16_f32 v42, v42, v43
	v_pk_mul_f32 v[46:47], v[218:219], v[46:47]
	s_nop 0
	v_cvt_pk_bf16_f32 v43, v46, v47
	global_store_dwordx2 v[38:39], v[42:43], off
	v_pk_mul_f32 v[42:43], v[50:51], v[34:35] op_sel_hi:[1,0]
	v_pk_mul_f32 v[0:1], v[220:221], v[0:1]
	v_pk_mul_f32 v[2:3], v[222:223], v[2:3]
	v_cvt_pk_bf16_f32 v0, v0, v1
	v_cvt_pk_bf16_f32 v1, v2, v3
	global_store_dwordx2 v[38:39], v[0:1], off offset:512
	v_pk_mul_f32 v[0:1], v[224:225], v[42:43]
	v_pk_mul_f32 v[42:43], v[44:45], v[34:35] op_sel_hi:[1,0]
	v_cvt_pk_bf16_f32 v0, v0, v1
	v_pk_mul_f32 v[2:3], v[226:227], v[42:43]
	v_pk_mul_f32 v[34:35], v[36:37], v[34:35] op_sel_hi:[1,0]
	v_cvt_pk_bf16_f32 v1, v2, v3
	global_store_dwordx2 v[38:39], v[0:1], off offset:1024
	v_mov_b64_e32 v[36:37], v[22:23]
	v_mov_b64_e32 v[42:43], v[30:31]
	v_mov_b64_e32 v[44:45], v[32:33]
	v_pk_mul_f32 v[0:1], v[228:229], v[40:41]
	v_pk_mul_f32 v[2:3], v[230:231], v[34:35]
	v_cvt_pk_bf16_f32 v0, v0, v1
	v_cvt_pk_bf16_f32 v1, v2, v3
	global_store_dwordx2 v[38:39], v[0:1], off offset:1536
	v_mov_b64_e32 v[0:1], v[18:19]
	v_mov_b64_e32 v[34:35], v[20:21]
	v_mov_b64_e32 v[40:41], v[24:25]
	v_mov_b64_e32 v[2:3], v[26:27]
	v_mov_b64_e32 v[38:39], v[28:29]
	s_andn2_b64 exec, exec, s[18:19]
	s_cbranch_execz .LBB0_235

; __device__ __forceinline__ int ltid() { int t = threadIdx.x; asm volatile("" : "+v"(t)); return t; }
; template <bool SRC_F32, bool DST_F32, bool HAS_H>
; __device__ __forceinline__ void phase_rowpass(const void* xp, const void* xs, const bf16* Y, float coef, const float* gpost, const float* gpre, void* xdst, bf16* H) {
;     const int tid = ltid(), lane = tid & 63, wave = tid >> 6;
;     const int gw = blockIdx.x * NWAVES + wave, NGW = gridDim.x * NWAVES;
;     f32x4 y[4], x[4], nxf[4]; u32x2 ny[4], nxb[4];
;     ...
;     if (gw < MR) RP_LOAD(gw);
;     for (int m = gw; m < MR; m += NGW) {
; #pragma unroll
;         for (int j = 0; j < 4; ++j) { y[j] = (f32x4){bflo(ny[j].x), bfhi(ny[j].x), bflo(ny[j].y), bfhi(ny[j].y)};
;             x[j] = SRC_F32 ? nxf[j] : (f32x4){bflo(nxb[j].x), bfhi(nxb[j].x), bflo(nxb[j].y), bfhi(nxb[j].y)}; }
;         if (m + NGW < MR) RP_LOAD(m + NGW);
;         float s = 0.f;
; #pragma unroll
;         for (int j = 0; j < 4; ++j) s += (y[j].x * y[j].x + y[j].y * y[j].y) + (y[j].z * y[j].z + y[j].w * y[j].w);
;         const float rstd = rsqrtf(wave_sum(s) * (1.f / D) + RMS_EPS) * coef;
;         float s2 = 0.f;
; #pragma unroll
;         for (int j = 0; j < 4; ++j) { const f32x4 gg = *((const f32x4*)gpost + lane + 64 * j);
;             x[j].x += y[j].x * rstd * gg.x; x[j].y += y[j].y * rstd * gg.y; x[j].z += y[j].z * rstd * gg.z; x[j].w += y[j].w * rstd * gg.w;
.LBB0_236:
	s_andn2_b64 vcc, exec, s[10:11]
	s_cbranch_vccnz .LBB0_243
	v_mov_b32_e32 v1, v172
	v_readlane_b32 s0, v253, 6
	v_ashrrev_i32_e32 v0, 6, v1
	s_nop 0
	v_add_u32_e32 v36, s0, v0
	v_cmp_gt_i32_e32 vcc, s93, v36
	s_and_saveexec_b64 s[20:21], vcc
	s_cbranch_execz .LBB0_242
	s_load_dwordx4 s[16:19], s[6:7], 0x0
	v_ashrrev_i32_e32 v37, 31, v36
	v_add_u32_e32 v140, 0xffff8000, v36
	v_lshlrev_b64 v[8:9], 12, v[36:37]
	v_lshlrev_b64 v[10:11], 12, v[140:141]
	v_and_b32_e32 v2, 63, v1
	v_lshlrev_b64 v[4:5], 11, v[36:37]
	s_waitcnt lgkmcnt(0)
	v_lshl_add_u64 v[8:9], s[16:17], 0, v[8:9]
	v_lshl_add_u64 v[10:11], s[18:19], 0, v[10:11]
	v_cmp_gt_i32_e32 vcc, s90, v36
	v_lshl_add_u64 v[6:7], s[8:9], 0, v[4:5]
	v_lshlrev_b32_e32 v38, 3, v2
	v_mov_b32_e32 v39, v141
	v_cndmask_b32_e32 v9, v11, v9, vcc
	v_cndmask_b32_e32 v8, v10, v8, vcc
	v_lshlrev_b32_e32 v140, 4, v2
	v_lshl_add_u64 v[6:7], v[6:7], 0, v[38:39]
	v_lshl_add_u64 v[8:9], v[8:9], 0, v[140:141]
	global_load_dwordx2 v[62:63], v[6:7], off offset:512
	global_load_dwordx2 v[34:35], v[6:7], off offset:1024
	global_load_dwordx2 v[32:33], v[6:7], off offset:1536
	global_load_dwordx4 v[16:19], v[8:9], off offset:3072
	global_load_dwordx4 v[20:23], v[8:9], off offset:2048
	global_load_dwordx4 v[24:27], v[8:9], off offset:1024
	global_load_dwordx4 v[28:31], v[8:9], off
	global_load_dwordx2 v[64:65], v[6:7], off
	v_readlane_b32 s0, v254, 21
	v_lshlrev_b32_e32 v40, 4, v2
	v_lshl_add_u64 v[2:3], s[4:5], 0, v[140:141]
	v_add_u32_e32 v0, s0, v0
	v_ashrrev_i32_e32 v1, 31, v0
	s_mov_b64 s[4:5], 0x1000
	v_lshl_add_u64 v[42:43], s[12:13], 0, v[4:5]
	v_lshl_add_u64 v[44:45], s[14:15], 0, v[4:5]
	v_lshlrev_b64 v[4:5], 11, v[0:1]
	v_lshlrev_b64 v[0:1], 12, v[0:1]
	v_lshl_add_u64 v[46:47], v[2:3], 0, s[4:5]
	s_mov_b64 s[4:5], 0x2000
	v_lshl_add_u64 v[48:49], v[2:3], 0, s[4:5]
	v_lshl_add_u64 v[50:51], s[14:15], 0, v[4:5]
	v_lshl_add_u64 v[52:53], s[16:17], 0, v[0:1]
	s_mov_b64 s[6:7], 0
	s_waitcnt vmcnt(4)
	v_mov_b64_e32 v[0:1], v[16:17]
	s_waitcnt vmcnt(3)
	v_mov_b64_e32 v[4:5], v[20:21]
	s_waitcnt vmcnt(2)
	v_mov_b64_e32 v[8:9], v[24:25]
	s_waitcnt vmcnt(1)
	v_mov_b64_e32 v[12:13], v[28:29]
	v_mov_b64_e32 v[54:55], v[32:33]
	v_mov_b64_e32 v[56:57], v[34:35]
	v_mov_b64_e32 v[58:59], v[62:63]
	v_mov_b64_e32 v[2:3], v[18:19]
	v_mov_b64_e32 v[6:7], v[22:23]
	v_mov_b64_e32 v[10:11], v[26:27]
	v_mov_b64_e32 v[14:15], v[30:31]
	s_waitcnt vmcnt(0)
	v_mov_b64_e32 v[60:61], v[64:65]
	global_load_dwordx4 v[200:203], v[46:47], off
	global_load_dwordx4 v[204:207], v[46:47], off offset:1024
	global_load_dwordx4 v[208:211], v[46:47], off offset:2048
	global_load_dwordx4 v[212:215], v[46:47], off offset:3072
	global_load_dwordx4 v[216:219], v[48:49], off
	global_load_dwordx4 v[220:223], v[48:49], off offset:1024
	global_load_dwordx4 v[224:227], v[48:49], off offset:2048
	global_load_dwordx4 v[228:231], v[48:49], off offset:3072
	s_waitcnt vmcnt(0)
	s_branch .LBB0_240
.LBB0_239:
	s_or_b64 exec, exec, s[4:5]
	v_and_b32_e32 v81, 0xffff0000, v64
	v_and_b32_e32 v79, 0xffff0000, v65
	v_lshlrev_b32_e32 v80, 16, v64
	v_lshlrev_b32_e32 v78, 16, v65
	v_lshlrev_b32_e32 v70, 16, v34
	v_and_b32_e32 v71, 0xffff0000, v34
	v_lshlrev_b32_e32 v68, 16, v35
	v_and_b32_e32 v69, 0xffff0000, v35
	v_mov_b32_e32 v34, v81
	v_mov_b32_e32 v35, v79
	v_lshlrev_b32_e32 v66, 16, v32
	v_and_b32_e32 v67, 0xffff0000, v32
	v_lshlrev_b32_e32 v64, 16, v33
	v_and_b32_e32 v65, 0xffff0000, v33
	v_mov_b32_e32 v32, v80
	v_mov_b32_e32 v33, v78
	v_pk_mul_f32 v[34:35], v[34:35], v[34:35]
	v_and_b32_e32 v75, 0xffff0000, v63
	v_pk_fma_f32 v[32:33], v[32:33], v[32:33], v[34:35]
	v_and_b32_e32 v74, 0xffff0000, v62
	v_pk_add_f32 v[32:33], v[32:33], v[32:33] op_sel_hi:[0,1]
	v_lshlrev_b32_e32 v77, 16, v63
	v_lshlrev_b32_e32 v76, 16, v62
	v_pk_mul_f32 v[34:35], v[74:75], v[74:75]
	v_mul_f32_e32 v32, v68, v68
	v_pk_fma_f32 v[34:35], v[76:77], v[76:77], v[34:35]
	v_pk_fma_f32 v[62:63], v[68:69], v[68:69], v[32:33] op_sel_hi:[1,1,0]
	v_mul_f32_e32 v32, v70, v70
	v_pk_add_f32 v[34:35], v[34:35], v[34:35] op_sel_hi:[0,1]
	v_pk_mul_f32 v[72:73], v[66:67], v[66:67]
	v_pk_mul_f32 v[82:83], v[64:65], v[64:65]
	v_pk_fma_f32 v[84:85], v[70:71], v[70:71], v[32:33] op_sel_hi:[1,1,0]
	v_mov_b32_e32 v62, v73
	v_mov_b32_e32 v84, v72
	v_mov_b32_e32 v34, v82
	v_mov_b32_e32 v32, v83
	v_pk_add_f32 v[62:63], v[84:85], v[62:63]
	v_pk_add_f32 v[32:33], v[34:35], v[32:33]
	s_mov_b32 s0, 0x5100000
	v_pk_add_f32 v[32:33], v[62:63], v[32:33]
	v_lshl_add_u64 v[62:63], v[42:43], 0, v[38:39]
	v_add_f32_e32 v32, v32, v33
	v_lshl_add_u64 v[42:43], v[42:43], 0, s[82:83]
	v_lshl_add_u64 v[50:51], v[50:51], 0, s[82:83]
	v_add_f32_dpp v32, v32, v32 quad_perm:[1,0,3,2] row_mask:0xf bank_mask:0xf bound_ctrl:1
	s_nop 1
	v_add_f32_dpp v32, v32, v32 quad_perm:[2,3,0,1] row_mask:0xf bank_mask:0xf bound_ctrl:1
	s_nop 1
	v_add_f32_dpp v32, v32, v32 row_half_mirror row_mask:0xf bank_mask:0xf bound_ctrl:1
	s_nop 1
	v_add_f32_dpp v32, v32, v32 row_mirror row_mask:0xf bank_mask:0xf bound_ctrl:1
	s_nop 0
	v_readlane_b32 s8, v32, 16
	v_readlane_b32 s9, v32, 48
	v_readlane_b32 s4, v32, 0
	v_readlane_b32 s5, v32, 32
	v_mov_b32_e32 v32, s8
	v_mov_b32_e32 v33, s9
	v_pk_add_f32 v[32:33], s[4:5], v[32:33]
	s_nop 0
	v_add_f32_e32 v32, v32, v33
	v_fmamk_f32 v32, v32, 0x3a800000, v177
	v_cmp_gt_f32_e32 vcc, s65, v32
	v_mul_f32_e32 v33, 0x4b800000, v32
	s_nop 0
	v_cndmask_b32_e32 v32, v32, v33, vcc
	v_rsq_f32_e32 v32, v32
	s_nop 0
	v_mul_f32_e32 v33, 0x45800000, v32
	v_cndmask_b32_e32 v32, v32, v33, vcc
	v_mul_f32_e32 v72, 0.5, v32
	v_pk_mul_f32 v[80:81], v[72:73], v[80:81] op_sel_hi:[0,1]
	v_pk_mul_f32 v[70:71], v[72:73], v[70:71] op_sel_hi:[0,1]
	v_pk_mul_f32 v[68:69], v[72:73], v[68:69] op_sel_hi:[0,1]
	v_pk_mul_f32 v[66:67], v[72:73], v[66:67] op_sel_hi:[0,1]
	v_pk_mul_f32 v[64:65], v[72:73], v[64:65] op_sel_hi:[0,1]
	s_waitcnt vmcnt(0)
; __device__ __forceinline__ unsigned pk2(float lo, float hi) { f32x2_t v = {lo, hi}; bf16x2_t b = __builtin_convertvector(v, bf16x2_t); return __builtin_bit_cast(unsigned, b); }
; template <bool SRC_F32, bool DST_F32, bool HAS_H>
; __device__ __forceinline__ void phase_rowpass(const void* xp, const void* xs, const bf16* Y, float coef, const float* gpost, const float* gpre, void* xdst, bf16* H) {
;     ...
;         for (int j = 0; j < 4; ++j) { const f32x4 gg = *((const f32x4*)gpost + lane + 64 * j);
;             x[j].x += y[j].x * rstd * gg.x; x[j].y += y[j].y * rstd * gg.y; x[j].z += y[j].z * rstd * gg.z; x[j].w += y[j].w * rstd * gg.w;
;             s2 += (x[j].x * x[j].x + x[j].y * x[j].y) + (x[j].z * x[j].z + x[j].w * x[j].w);
;             if (DST_F32) *((f32x4*)((float*)xdst + (size_t)m * D) + lane + 64 * j) = x[j];
;             else { u32x2 o; o.x = pk2(x[j].x, x[j].y); o.y = pk2(x[j].z, x[j].w); *((u32x2*)((bf16*)xdst + (size_t)m * D) + lane + 64 * j) = o; } }
;         if (HAS_H) {
;             const float r2 = rsqrtf(wave_sum(s2) * (1.f / D) + RMS_EPS);
; #pragma unroll
;             for (int j = 0; j < 4; ++j) { const f32x4 gg = *((const f32x4*)gpre + lane + 64 * j); u32x2 o; o.x = pk2(x[j].x * r2 * gg.x, x[j].y * r2 * gg.y); o.y = pk2(x[j].z * r2 * gg.z, x[j].w * r2 * gg.w);
;                 *((u32x2*)(H + (size_t)m * D) + lane + 64 * j) = o; }
	v_pk_fma_f32 v[32:33], v[200:201], v[80:81], v[28:29]
	v_pk_mul_f32 v[28:29], v[72:73], v[78:79] op_sel_hi:[0,1]
	v_pk_fma_f32 v[30:31], v[202:203], v[28:29], v[30:31]
	v_mov_b32_e32 v34, v33
	v_mov_b32_e32 v35, v31
	v_mov_b32_e32 v28, v32
	v_mov_b32_e32 v29, v30
	v_pk_mul_f32 v[34:35], v[34:35], v[34:35]
	s_nop 0
	v_pk_fma_f32 v[28:29], v[28:29], v[28:29], v[34:35]
	v_cvt_pk_bf16_f32 v34, v32, v33
	v_cvt_pk_bf16_f32 v35, v30, v31
	global_store_dwordx2 v[62:63], v[34:35], off
	v_mov_b32_e32 v34, v76
	v_mov_b32_e32 v35, v74
	v_pk_mul_f32 v[34:35], v[72:73], v[34:35] op_sel_hi:[0,1]
	v_mov_b32_e32 v74, v77
	v_pk_add_f32 v[28:29], v[28:29], v[28:29] op_sel_hi:[0,1]
	v_pk_fma_f32 v[24:25], v[204:205], v[34:35], v[24:25]
	v_pk_mul_f32 v[34:35], v[72:73], v[74:75] op_sel_hi:[0,1]
	v_pk_fma_f32 v[26:27], v[206:207], v[34:35], v[26:27]
	v_mov_b32_e32 v74, v25
	v_mov_b32_e32 v75, v27
	v_mov_b32_e32 v34, v24
	v_mov_b32_e32 v35, v26
	v_pk_mul_f32 v[74:75], v[74:75], v[74:75]
	s_nop 0
	v_pk_fma_f32 v[34:35], v[34:35], v[34:35], v[74:75]
	v_cvt_pk_bf16_f32 v74, v24, v25
	v_cvt_pk_bf16_f32 v75, v26, v27
	global_store_dwordx2 v[62:63], v[74:75], off offset:512
	v_pk_add_f32 v[34:35], v[34:35], v[34:35] op_sel_hi:[0,1]
	v_pk_fma_f32 v[20:21], v[208:209], v[70:71], v[20:21]
	v_pk_fma_f32 v[22:23], v[210:211], v[68:69], v[22:23]
	v_cvt_pk_bf16_f32 v68, v20, v21
	v_cvt_pk_bf16_f32 v69, v22, v23
	global_store_dwordx2 v[62:63], v[68:69], off offset:1024
	v_mul_f32_e32 v28, v20, v20
	v_pk_fma_f32 v[74:75], v[20:21], v[20:21], v[28:29] op_sel_hi:[1,1,0]
	v_mul_f32_e32 v28, v22, v22
	v_pk_fma_f32 v[76:77], v[22:23], v[22:23], v[28:29] op_sel_hi:[1,1,0]
	v_pk_fma_f32 v[16:17], v[212:213], v[66:67], v[16:17]
	v_pk_fma_f32 v[18:19], v[214:215], v[64:65], v[18:19]
	v_pk_mul_f32 v[64:65], v[16:17], v[16:17]
	v_pk_mul_f32 v[66:67], v[18:19], v[18:19]
	v_mov_b32_e32 v74, v64
	v_mov_b32_e32 v76, v65
	v_mov_b32_e32 v28, v66
	v_mov_b32_e32 v34, v67
	v_pk_add_f32 v[64:65], v[74:75], v[76:77]
	v_pk_add_f32 v[28:29], v[28:29], v[34:35]
	s_nop 0
	v_pk_add_f32 v[28:29], v[64:65], v[28:29]
	s_nop 0
	v_add_f32_e32 v34, v28, v29
	v_cvt_pk_bf16_f32 v28, v16, v17
	v_cvt_pk_bf16_f32 v29, v18, v19
	global_store_dwordx2 v[62:63], v[28:29], off offset:1536
	v_add_f32_dpp v28, v34, v34 quad_perm:[1,0,3,2] row_mask:0xf bank_mask:0xf bound_ctrl:1
	v_lshl_add_u64 v[34:35], v[44:45], 0, v[38:39]
	v_lshl_add_u64 v[44:45], v[44:45], 0, s[82:83]
	v_add_f32_dpp v28, v28, v28 quad_perm:[2,3,0,1] row_mask:0xf bank_mask:0xf bound_ctrl:1
	s_nop 1
	v_add_f32_dpp v28, v28, v28 row_half_mirror row_mask:0xf bank_mask:0xf bound_ctrl:1
	s_nop 1
	v_add_f32_dpp v28, v28, v28 row_mirror row_mask:0xf bank_mask:0xf bound_ctrl:1
	s_nop 0
	v_readlane_b32 s8, v28, 16
	v_readlane_b32 s9, v28, 48
	v_readlane_b32 s4, v28, 0
	v_readlane_b32 s5, v28, 32
	v_mov_b32_e32 v28, s8
	v_mov_b32_e32 v29, s9
	v_pk_add_f32 v[28:29], s[4:5], v[28:29]
	v_readlane_b32 s4, v254, 41
	v_add_f32_e32 v28, v28, v29
	v_fmamk_f32 v28, v28, 0x3a800000, v177
	v_cmp_gt_f32_e32 vcc, s65, v28
	v_mul_f32_e32 v29, 0x4b800000, v28
	v_readlane_b32 s5, v254, 42
	v_cndmask_b32_e32 v28, v28, v29, vcc
	v_rsq_f32_e32 v28, v28
	v_lshl_add_u64 v[52:53], v[52:53], 0, s[4:5]
	v_mul_f32_e32 v29, 0x45800000, v28
	v_cndmask_b32_e32 v28, v28, v29, vcc
	v_pk_mul_f32 v[32:33], v[32:33], v[28:29] op_sel_hi:[1,0]
	v_pk_mul_f32 v[30:31], v[30:31], v[28:29] op_sel_hi:[1,0]
	v_add_co_u32_e32 v34, vcc, s0, v34
	v_pk_mul_f32 v[24:25], v[24:25], v[28:29] op_sel_hi:[1,0]
	s_nop 0
	v_addc_co_u32_e32 v35, vcc, 0, v35, vcc
	v_pk_mul_f32 v[26:27], v[26:27], v[28:29] op_sel_hi:[1,0]
	v_pk_mul_f32 v[20:21], v[20:21], v[28:29] op_sel_hi:[1,0]
	v_pk_mul_f32 v[22:23], v[22:23], v[28:29] op_sel_hi:[1,0]
	v_pk_mul_f32 v[16:17], v[16:17], v[28:29] op_sel_hi:[1,0]
	v_pk_mul_f32 v[18:19], v[18:19], v[28:29] op_sel_hi:[1,0]
	v_pk_mul_f32 v[32:33], v[216:217], v[32:33]
	v_pk_mul_f32 v[30:31], v[218:219], v[30:31]
	v_cvt_pk_bf16_f32 v32, v32, v33
	v_cvt_pk_bf16_f32 v33, v30, v31
	global_store_dwordx2 v[34:35], v[32:33], off
	v_mov_b64_e32 v[62:63], v[58:59]
	v_mov_b64_e32 v[64:65], v[60:61]
	v_pk_mul_f32 v[24:25], v[220:221], v[24:25]
	v_pk_mul_f32 v[26:27], v[222:223], v[26:27]
	v_cvt_pk_bf16_f32 v24, v24, v25
	v_cvt_pk_bf16_f32 v25, v26, v27
	global_store_dwordx2 v[34:35], v[24:25], off offset:512
	v_mov_b64_e32 v[30:31], v[14:15]
	v_mov_b64_e32 v[28:29], v[12:13]
	v_mov_b64_e32 v[32:33], v[54:55]
	v_pk_mul_f32 v[20:21], v[224:225], v[20:21]
	v_pk_mul_f32 v[22:23], v[226:227], v[22:23]
	v_cvt_pk_bf16_f32 v20, v20, v21
	v_cvt_pk_bf16_f32 v21, v22, v23
	global_store_dwordx2 v[34:35], v[20:21], off offset:1024
	v_mov_b64_e32 v[26:27], v[10:11]
	v_mov_b64_e32 v[24:25], v[8:9]
	v_pk_mul_f32 v[16:17], v[228:229], v[16:17]
	v_pk_mul_f32 v[18:19], v[230:231], v[18:19]
	v_cvt_pk_bf16_f32 v16, v16, v17
	v_cvt_pk_bf16_f32 v17, v18, v19
	global_store_dwordx2 v[34:35], v[16:17], off offset:1536
	v_mov_b64_e32 v[18:19], v[2:3]
	v_mov_b64_e32 v[22:23], v[6:7]
	v_mov_b64_e32 v[16:17], v[0:1]
	v_mov_b64_e32 v[20:21], v[4:5]
	v_mov_b64_e32 v[34:35], v[56:57]
	s_andn2_b64 exec, exec, s[6:7]
	s_cbranch_execz .LBB0_242

; __device__ __forceinline__ unsigned pk2(float lo, float hi) { f32x2_t v = {lo, hi}; bf16x2_t b = __builtin_convertvector(v, bf16x2_t); return __builtin_bit_cast(unsigned, b); }
; __device__ __forceinline__ void rwkv_prep_part(const Args& a, int l, unsigned char* lds) {
;     ...
;     const int lane = tid & 63, c = tid & 255, half = tid >> 8, h = c >> 6, cc = c & 63;
;     const float* mu = in_I_MU + (size_t)l * RW;
;     const float mur = mu[c], muk = mu[256 + c], muv = mu[512 + c];
;     const float w0c = in_I_W0[l * 256 + c], a0c = in_I_A0[l * 256 + c], kkc = in_I_KK[l * 256 + c], kac = in_I_KA[l * 256 + c], rkc = in_I_RK[l * 256 + c];
;     unsigned w2p[16], a2p[16], g2p[32];
; #pragma unroll
;     for (int i = 0; i < 16; ++i) { w2p[i] = pk2(in_I_W2[(size_t)(l * 32 + 2 * i) * 256 + c], in_I_W2[(size_t)(l * 32 + 2 * i + 1) * 256 + c]);
;                                    a2p[i] = pk2(in_I_A2[(size_t)(l * 32 + 2 * i) * 256 + c], in_I_A2[(size_t)(l * 32 + 2 * i + 1) * 256 + c]); }
.LBB0_487:
	s_or_b64 exec, exec, s[4:5]
	v_readlane_b32 s4, v255, 4
	v_readlane_b32 s5, v255, 5
	v_readlane_b32 s6, v253, 38
	s_lshl_b32 s50, s4, 8
	s_lshl_b32 s51, s4, 14
	v_readlane_b32 s4, v253, 2
	v_readlane_b32 s7, v253, 39
	v_mov_b32_e32 v10, v172
	v_readlane_b32 s5, v253, 3
	s_andn2_b64 vcc, exec, s[6:7]
	s_cbranch_vccnz .LBB0_587
	s_load_dwordx4 s[28:31], s[4:5], 0xe0
	s_load_dwordx16 s[12:27], s[4:5], 0x80
	v_readlane_b32 s6, v255, 4
	s_mul_i32 s78, s6, 0x380
	s_load_dwordx2 s[10:11], s[4:5], 0xc0
	s_load_dwordx2 s[8:9], s[4:5], 0x28
	s_lshl_b64 s[4:5], s[78:79], 2
	v_readlane_b32 s7, v255, 5
	s_mov_b32 s0, s6
	v_and_b32_e32 v0, 0xff, v10
	s_waitcnt lgkmcnt(0)
	s_add_u32 s6, s12, s4
	s_addc_u32 s7, s13, s5
	v_lshlrev_b32_e32 v4, 2, v0
	v_or_b32_e32 v140, s50, v0
	global_load_dword v1, v4, s[6:7]
	global_load_dword v24, v4, s[6:7] offset:1024
	global_load_dword v25, v4, s[6:7] offset:2048
	v_lshlrev_b64 v[4:5], 2, v[140:141]
	v_lshl_add_u64 v[6:7], s[14:15], 0, v[4:5]
	global_load_dword v26, v[6:7], off
	v_lshl_add_u64 v[6:7], s[18:19], 0, v[4:5]
	global_load_dword v27, v[6:7], off
	v_lshl_add_u64 v[6:7], s[24:25], 0, v[4:5]
	global_load_dword v28, v[6:7], off
	v_lshl_add_u64 v[6:7], s[26:27], 0, v[4:5]
	v_lshl_add_u64 v[4:5], s[10:11], 0, v[4:5]
	v_lshl_or_b32 v140, s0, 13, v0
	global_load_dword v30, v[4:5], off
	v_lshlrev_b64 v[4:5], 2, v[140:141]
	global_load_dword v29, v[6:7], off
	v_lshl_add_u64 v[6:7], s[16:17], 0, v[4:5]
	global_load_dword v204, v[6:7], off
	global_load_dword v205, v[6:7], off offset:1024
	v_lshl_add_u64 v[4:5], s[20:21], 0, v[4:5]
	v_mov_b32_e32 v2, s22
	v_mov_b32_e32 v3, s23
	s_movk_i32 s0, 0x1000
	s_add_u32 s4, s30, 0x9180000
	s_addc_u32 s5, s31, 0
	v_bfe_u32 v94, v10, 6, 2
	v_add_u32_e32 v13, 0x200, v10
	v_ashrrev_i32_e32 v12, 5, v10
	v_ashrrev_i32_e32 v97, 7, v10
	v_lshl_add_u32 v99, v10, 1, 0
	v_ashrrev_i32_e32 v100, 7, v13
	v_add_u32_e32 v13, 0x400, v10
	v_and_b32_e32 v95, -8, v12
	v_and_b32_e32 v96, 8, v12
	v_ashrrev_i32_e32 v102, 7, v13
	v_lshl_or_b32 v14, v12, 8, v181
	v_and_b32_e32 v98, 15, v97
	v_and_b32_e32 v101, 15, v100
	v_and_b32_e32 v103, 15, v102
	v_lshl_add_u32 v106, v95, 8, 0
	v_add_u32_e32 v107, 0, v14
	v_readlane_b32 s24, v254, 19
	global_load_dword v206, v[4:5], off
	global_load_dword v207, v[4:5], off offset:1024
	global_load_dword v208, v[6:7], off offset:2048
	s_nop 0
	global_load_dword v209, v[6:7], off offset:3072
	global_load_dword v210, v[4:5], off offset:2048
	s_nop 0
	global_load_dword v211, v[4:5], off offset:3072
	v_mov_b32_e32 v5, v141
	v_or_b32_e32 v4, 0x400, v140
	v_lshlrev_b64 v[4:5], 2, v[4:5]
	v_lshl_add_u64 v[6:7], s[16:17], 0, v[4:5]
	global_load_dword v212, v[6:7], off
	v_or_b32_e32 v6, 0x500, v140
	v_mov_b32_e32 v7, v141
	v_lshlrev_b64 v[6:7], 2, v[6:7]
	v_lshl_add_u64 v[8:9], s[16:17], 0, v[6:7]
	global_load_dword v213, v[8:9], off
	v_lshl_add_u64 v[4:5], s[20:21], 0, v[4:5]
	global_load_dword v214, v[4:5], off
	v_lshl_add_u64 v[4:5], s[20:21], 0, v[6:7]
	global_load_dword v215, v[4:5], off
	v_mov_b32_e32 v5, v141
	v_or_b32_e32 v4, 0x600, v140
	v_lshlrev_b64 v[4:5], 2, v[4:5]
	v_lshl_add_u64 v[6:7], s[16:17], 0, v[4:5]
	global_load_dword v216, v[6:7], off
	v_or_b32_e32 v6, 0x700, v140
	v_mov_b32_e32 v7, v141
	v_lshlrev_b64 v[6:7], 2, v[6:7]
	v_lshl_add_u64 v[8:9], s[16:17], 0, v[6:7]
	global_load_dword v217, v[8:9], off
	v_lshl_add_u64 v[4:5], s[20:21], 0, v[4:5]
	global_load_dword v218, v[4:5], off
	v_lshl_add_u64 v[4:5], s[20:21], 0, v[6:7]
	global_load_dword v219, v[4:5], off
	v_mov_b32_e32 v5, v141
	v_or_b32_e32 v4, 0x800, v140
	v_lshlrev_b64 v[4:5], 2, v[4:5]
	v_lshl_add_u64 v[6:7], s[16:17], 0, v[4:5]
	global_load_dword v220, v[6:7], off
	v_or_b32_e32 v6, 0x900, v140
	v_mov_b32_e32 v7, v141
	v_lshlrev_b64 v[6:7], 2, v[6:7]
	v_lshl_add_u64 v[8:9], s[16:17], 0, v[6:7]
	global_load_dword v221, v[8:9], off
	v_lshl_add_u64 v[4:5], s[20:21], 0, v[4:5]
	global_load_dword v222, v[4:5], off
	v_lshl_add_u64 v[4:5], s[20:21], 0, v[6:7]
	global_load_dword v223, v[4:5], off
	v_mov_b32_e32 v5, v141
	v_or_b32_e32 v4, 0xa00, v140
	v_lshlrev_b64 v[4:5], 2, v[4:5]
	v_lshl_add_u64 v[6:7], s[16:17], 0, v[4:5]
	global_load_dword v224, v[6:7], off
	v_or_b32_e32 v6, 0xb00, v140
	v_mov_b32_e32 v7, v141
	v_lshlrev_b64 v[6:7], 2, v[6:7]
	v_lshl_add_u64 v[8:9], s[16:17], 0, v[6:7]
	global_load_dword v225, v[8:9], off
	v_lshl_add_u64 v[4:5], s[20:21], 0, v[4:5]
	global_load_dword v226, v[4:5], off
	v_lshl_add_u64 v[4:5], s[20:21], 0, v[6:7]
	global_load_dword v227, v[4:5], off
	v_mov_b32_e32 v5, v141
	v_or_b32_e32 v4, 0xc00, v140
	v_lshlrev_b64 v[4:5], 2, v[4:5]
	v_lshl_add_u64 v[6:7], s[16:17], 0, v[4:5]
	global_load_dword v228, v[6:7], off
	v_or_b32_e32 v6, 0xd00, v140
	v_mov_b32_e32 v7, v141
	v_lshlrev_b64 v[6:7], 2, v[6:7]
	v_lshl_add_u64 v[8:9], s[16:17], 0, v[6:7]
	global_load_dword v229, v[8:9], off
	v_lshl_add_u64 v[4:5], s[20:21], 0, v[4:5]
	global_load_dword v230, v[4:5], off
	v_lshl_add_u64 v[4:5], s[20:21], 0, v[6:7]
	global_load_dword v231, v[4:5], off
	v_mov_b32_e32 v5, v141
	v_or_b32_e32 v4, 0xe00, v140
	v_lshlrev_b64 v[4:5], 2, v[4:5]
	v_lshl_add_u64 v[6:7], s[16:17], 0, v[4:5]
	global_load_dword v232, v[6:7], off
	v_or_b32_e32 v6, 0xf00, v140
	v_mov_b32_e32 v7, v141
	v_lshlrev_b64 v[6:7], 2, v[6:7]
	v_lshl_add_u64 v[8:9], s[16:17], 0, v[6:7]
	global_load_dword v233, v[8:9], off
	v_lshl_add_u64 v[4:5], s[20:21], 0, v[4:5]
	global_load_dword v234, v[4:5], off
	v_lshl_add_u64 v[4:5], s[20:21], 0, v[6:7]
	global_load_dword v235, v[4:5], off
	v_mov_b32_e32 v5, v141
	s_waitcnt vmcnt(0)
; __device__ __forceinline__ unsigned pk2(float lo, float hi) { f32x2_t v = {lo, hi}; bf16x2_t b = __builtin_convertvector(v, bf16x2_t); return __builtin_bit_cast(unsigned, b); }
; __device__ __forceinline__ void rwkv_prep_part(const Args& a, int l, unsigned char* lds) {
;     ...
;     unsigned w2p[16], a2p[16], g2p[32];
; #pragma unroll
;     for (int i = 0; i < 16; ++i) { w2p[i] = pk2(in_I_W2[(size_t)(l * 32 + 2 * i) * 256 + c], in_I_W2[(size_t)(l * 32 + 2 * i + 1) * 256 + c]);
;                                    a2p[i] = pk2(in_I_A2[(size_t)(l * 32 + 2 * i) * 256 + c], in_I_A2[(size_t)(l * 32 + 2 * i + 1) * 256 + c]); }
; #pragma unroll
;     for (int i = 0; i < 32; ++i) g2p[i] = pk2(in_I_G2[(size_t)(l * 64 + 2 * i) * 256 + c], in_I_G2[(size_t)(l * 64 + 2 * i + 1) * 256 + c]);
	v_cvt_pk_bf16_f32 v31, v204, v205
	v_cvt_pk_bf16_f32 v32, v206, v207
	v_cvt_pk_bf16_f32 v33, v208, v209
	v_cvt_pk_bf16_f32 v34, v210, v211
	v_cvt_pk_bf16_f32 v35, v212, v213
	v_cvt_pk_bf16_f32 v36, v214, v215
	v_cvt_pk_bf16_f32 v37, v216, v217
	v_cvt_pk_bf16_f32 v38, v218, v219
	v_cvt_pk_bf16_f32 v39, v220, v221
	v_cvt_pk_bf16_f32 v40, v222, v223
	v_cvt_pk_bf16_f32 v41, v224, v225
	v_cvt_pk_bf16_f32 v42, v226, v227
	v_cvt_pk_bf16_f32 v43, v228, v229
	v_cvt_pk_bf16_f32 v44, v230, v231
	v_cvt_pk_bf16_f32 v45, v232, v233
	v_cvt_pk_bf16_f32 v46, v234, v235
	v_or_b32_e32 v4, 0x1000, v140
	v_lshlrev_b64 v[4:5], 2, v[4:5]
	v_lshl_add_u64 v[6:7], s[16:17], 0, v[4:5]
	global_load_dword v204, v[6:7], off
	v_or_b32_e32 v6, 0x1100, v140
	v_mov_b32_e32 v7, v141
	v_lshlrev_b64 v[6:7], 2, v[6:7]
	v_lshl_add_u64 v[8:9], s[16:17], 0, v[6:7]
	global_load_dword v205, v[8:9], off
	v_lshl_add_u64 v[4:5], s[20:21], 0, v[4:5]
	global_load_dword v206, v[4:5], off
	v_lshl_add_u64 v[4:5], s[20:21], 0, v[6:7]
	global_load_dword v207, v[4:5], off
	v_mov_b32_e32 v5, v141
	v_or_b32_e32 v4, 0x1200, v140
	v_lshlrev_b64 v[4:5], 2, v[4:5]
	v_lshl_add_u64 v[6:7], s[16:17], 0, v[4:5]
	global_load_dword v208, v[6:7], off
	v_or_b32_e32 v6, 0x1300, v140
	v_mov_b32_e32 v7, v141
	v_lshlrev_b64 v[6:7], 2, v[6:7]
	v_lshl_add_u64 v[8:9], s[16:17], 0, v[6:7]
	global_load_dword v209, v[8:9], off
	v_lshl_add_u64 v[4:5], s[20:21], 0, v[4:5]
	global_load_dword v210, v[4:5], off
	v_lshl_add_u64 v[4:5], s[20:21], 0, v[6:7]
	global_load_dword v211, v[4:5], off
	v_mov_b32_e32 v5, v141
	v_or_b32_e32 v4, 0x1400, v140
	v_lshlrev_b64 v[4:5], 2, v[4:5]
	v_lshl_add_u64 v[6:7], s[16:17], 0, v[4:5]
	global_load_dword v212, v[6:7], off
	v_or_b32_e32 v6, 0x1500, v140
	v_mov_b32_e32 v7, v141
	v_lshlrev_b64 v[6:7], 2, v[6:7]
	v_lshl_add_u64 v[8:9], s[16:17], 0, v[6:7]
	global_load_dword v213, v[8:9], off
	v_lshl_add_u64 v[4:5], s[20:21], 0, v[4:5]
	global_load_dword v214, v[4:5], off
	v_lshl_add_u64 v[4:5], s[20:21], 0, v[6:7]
	global_load_dword v215, v[4:5], off
	v_mov_b32_e32 v5, v141
	v_or_b32_e32 v4, 0x1600, v140
	v_lshlrev_b64 v[4:5], 2, v[4:5]
	v_lshl_add_u64 v[6:7], s[16:17], 0, v[4:5]
	global_load_dword v216, v[6:7], off
	v_or_b32_e32 v6, 0x1700, v140
	v_mov_b32_e32 v7, v141
	v_lshlrev_b64 v[6:7], 2, v[6:7]
	v_lshl_add_u64 v[8:9], s[16:17], 0, v[6:7]
	global_load_dword v217, v[8:9], off
	v_lshl_add_u64 v[4:5], s[20:21], 0, v[4:5]
	global_load_dword v218, v[4:5], off
	v_lshl_add_u64 v[4:5], s[20:21], 0, v[6:7]
	global_load_dword v219, v[4:5], off
	v_mov_b32_e32 v5, v141
	v_or_b32_e32 v4, 0x1800, v140
	v_lshlrev_b64 v[4:5], 2, v[4:5]
	v_lshl_add_u64 v[6:7], s[16:17], 0, v[4:5]
	global_load_dword v220, v[6:7], off
	v_or_b32_e32 v6, 0x1900, v140
	v_mov_b32_e32 v7, v141
	v_lshlrev_b64 v[6:7], 2, v[6:7]
	v_lshl_add_u64 v[8:9], s[16:17], 0, v[6:7]
	global_load_dword v221, v[8:9], off
	v_lshl_add_u64 v[4:5], s[20:21], 0, v[4:5]
	global_load_dword v222, v[4:5], off
	v_lshl_add_u64 v[4:5], s[20:21], 0, v[6:7]
	global_load_dword v223, v[4:5], off
	v_mov_b32_e32 v5, v141
	v_or_b32_e32 v4, 0x1a00, v140
	v_lshlrev_b64 v[4:5], 2, v[4:5]
	v_lshl_add_u64 v[6:7], s[16:17], 0, v[4:5]
	global_load_dword v224, v[6:7], off
	v_or_b32_e32 v6, 0x1b00, v140
	v_mov_b32_e32 v7, v141
	v_lshlrev_b64 v[6:7], 2, v[6:7]
	v_lshl_add_u64 v[8:9], s[16:17], 0, v[6:7]
	global_load_dword v225, v[8:9], off
	v_lshl_add_u64 v[4:5], s[20:21], 0, v[4:5]
	global_load_dword v226, v[4:5], off
	v_lshl_add_u64 v[4:5], s[20:21], 0, v[6:7]
	global_load_dword v227, v[4:5], off
	v_mov_b32_e32 v5, v141
	v_or_b32_e32 v4, 0x1c00, v140
	v_lshlrev_b64 v[4:5], 2, v[4:5]
	v_lshl_add_u64 v[6:7], s[16:17], 0, v[4:5]
	global_load_dword v228, v[6:7], off
	v_or_b32_e32 v6, 0x1d00, v140
	v_mov_b32_e32 v7, v141
	v_lshlrev_b64 v[6:7], 2, v[6:7]
	v_lshl_add_u64 v[8:9], s[16:17], 0, v[6:7]
	global_load_dword v229, v[8:9], off
	v_lshl_add_u64 v[4:5], s[20:21], 0, v[4:5]
	global_load_dword v230, v[4:5], off
	v_lshl_add_u64 v[4:5], s[20:21], 0, v[6:7]
	global_load_dword v231, v[4:5], off
	v_mov_b32_e32 v5, v141
	v_or_b32_e32 v4, 0x1e00, v140
	v_lshlrev_b64 v[4:5], 2, v[4:5]
	v_lshl_add_u64 v[6:7], s[16:17], 0, v[4:5]
	v_or_b32_e32 v140, 0x1f00, v140
	global_load_dword v232, v[6:7], off
	v_lshlrev_b64 v[6:7], 2, v[140:141]
	v_lshl_add_u64 v[8:9], s[16:17], 0, v[6:7]
	global_load_dword v233, v[8:9], off
	v_lshl_add_u64 v[4:5], s[20:21], 0, v[4:5]
	v_or_b32_e32 v140, s51, v0
	v_lshl_add_u64 v[2:3], v[140:141], 2, v[2:3]
	global_load_dword v234, v[4:5], off
	v_lshl_add_u64 v[4:5], s[20:21], 0, v[6:7]
	global_load_dword v235, v[4:5], off
	v_and_b32_e32 v11, 63, v10
	s_add_u32 s20, s28, 0x10352000
	s_addc_u32 s21, s29, 0
	v_cmp_eq_u32_e64 s[14:15], 0, v11
	s_add_u32 s22, s28, 0x10180000
	s_addc_u32 s23, s29, 0
	s_waitcnt vmcnt(0)
; __device__ __forceinline__ unsigned pk2(float lo, float hi) { f32x2_t v = {lo, hi}; bf16x2_t b = __builtin_convertvector(v, bf16x2_t); return __builtin_bit_cast(unsigned, b); }
; __device__ __forceinline__ void rwkv_prep_part(const Args& a, int l, unsigned char* lds) {
;     ...
;     for (int i = 0; i < 16; ++i) { w2p[i] = pk2(in_I_W2[(size_t)(l * 32 + 2 * i) * 256 + c], in_I_W2[(size_t)(l * 32 + 2 * i + 1) * 256 + c]);
;                                    a2p[i] = pk2(in_I_A2[(size_t)(l * 32 + 2 * i) * 256 + c], in_I_A2[(size_t)(l * 32 + 2 * i + 1) * 256 + c]); }
; #pragma unroll
;     for (int i = 0; i < 32; ++i) g2p[i] = pk2(in_I_G2[(size_t)(l * 64 + 2 * i) * 256 + c], in_I_G2[(size_t)(l * 64 + 2 * i + 1) * 256 + c]);
	v_cvt_pk_bf16_f32 v47, v204, v205
	v_cvt_pk_bf16_f32 v48, v206, v207
	v_cvt_pk_bf16_f32 v49, v208, v209
	v_cvt_pk_bf16_f32 v50, v210, v211
	v_cvt_pk_bf16_f32 v51, v212, v213
	v_cvt_pk_bf16_f32 v52, v214, v215
	v_cvt_pk_bf16_f32 v53, v216, v217
	v_cvt_pk_bf16_f32 v54, v218, v219
	v_cvt_pk_bf16_f32 v55, v220, v221
	v_cvt_pk_bf16_f32 v56, v222, v223
	v_cvt_pk_bf16_f32 v57, v224, v225
	v_cvt_pk_bf16_f32 v58, v226, v227
	v_cvt_pk_bf16_f32 v59, v228, v229
	v_cvt_pk_bf16_f32 v60, v230, v231
	v_cvt_pk_bf16_f32 v61, v232, v233
	v_cvt_pk_bf16_f32 v62, v234, v235
	global_load_dword v204, v[2:3], off
	global_load_dword v205, v[2:3], off offset:1024
	global_load_dword v206, v[2:3], off offset:2048
	global_load_dword v207, v[2:3], off offset:3072
	v_add_co_u32_e32 v4, vcc, s0, v2
	s_movk_i32 s0, 0x2000
	s_nop 0
	v_addc_co_u32_e32 v5, vcc, 0, v3, vcc
	v_add_co_u32_e32 v6, vcc, s0, v2
	s_movk_i32 s0, 0x3000
	s_nop 0
	v_addc_co_u32_e32 v7, vcc, 0, v3, vcc
	global_load_dword v208, v[6:7], off offset:-4096
	global_load_dword v209, v[4:5], off offset:1024
	global_load_dword v210, v[4:5], off offset:2048
	s_nop 0
	global_load_dword v211, v[4:5], off offset:3072
	global_load_dword v212, v[6:7], off
	global_load_dword v213, v[6:7], off offset:1024
	global_load_dword v214, v[6:7], off offset:2048
	global_load_dword v215, v[6:7], off offset:3072
	v_add_co_u32_e32 v4, vcc, s0, v2
	s_movk_i32 s0, 0x4000
	s_nop 0
	v_addc_co_u32_e32 v5, vcc, 0, v3, vcc
	v_add_co_u32_e32 v6, vcc, s0, v2
	s_movk_i32 s0, 0x5000
	s_nop 0
	v_addc_co_u32_e32 v7, vcc, 0, v3, vcc
	global_load_dword v216, v[6:7], off offset:-4096
	global_load_dword v217, v[4:5], off offset:1024
	global_load_dword v218, v[4:5], off offset:2048
	s_nop 0
	global_load_dword v219, v[4:5], off offset:3072
	global_load_dword v220, v[6:7], off
	global_load_dword v221, v[6:7], off offset:1024
	global_load_dword v222, v[6:7], off offset:2048
	global_load_dword v223, v[6:7], off offset:3072
	v_add_co_u32_e32 v4, vcc, s0, v2
	s_movk_i32 s0, 0x6000
	s_nop 0
	v_addc_co_u32_e32 v5, vcc, 0, v3, vcc
	v_add_co_u32_e32 v6, vcc, s0, v2
	s_movk_i32 s0, 0x7000
	s_nop 0
	v_addc_co_u32_e32 v7, vcc, 0, v3, vcc
	global_load_dword v224, v[6:7], off offset:-4096
	global_load_dword v225, v[4:5], off offset:1024
	global_load_dword v226, v[4:5], off offset:2048
	s_nop 0
	global_load_dword v227, v[4:5], off offset:3072
	global_load_dword v228, v[6:7], off
	global_load_dword v229, v[6:7], off offset:1024
	global_load_dword v230, v[6:7], off offset:2048
	global_load_dword v231, v[6:7], off offset:3072
	v_add_co_u32_e32 v4, vcc, s0, v2
	s_mov_b32 s0, 0x9000
	s_nop 0
	v_addc_co_u32_e32 v5, vcc, 0, v3, vcc
	v_add_co_u32_e32 v6, vcc, s90, v2
	s_nop 1
	v_addc_co_u32_e32 v7, vcc, 0, v3, vcc
	global_load_dword v232, v[6:7], off offset:-4096
	global_load_dword v233, v[4:5], off offset:1024
	global_load_dword v234, v[4:5], off offset:2048
	s_nop 0
	global_load_dword v235, v[4:5], off offset:3072
	s_waitcnt vmcnt(0)
; __device__ __forceinline__ unsigned pk2(float lo, float hi) { f32x2_t v = {lo, hi}; bf16x2_t b = __builtin_convertvector(v, bf16x2_t); return __builtin_bit_cast(unsigned, b); }
; __device__ __forceinline__ void rwkv_prep_part(const Args& a, int l, unsigned char* lds) {
;     ...
; #pragma unroll
;     for (int i = 0; i < 32; ++i) g2p[i] = pk2(in_I_G2[(size_t)(l * 64 + 2 * i) * 256 + c], in_I_G2[(size_t)(l * 64 + 2 * i + 1) * 256 + c]);
;     constexpr int TPI = 16, TPH = 8;
;     const bool x8 = (gridDim.x & 7) == 0;
;     constexpr int IPS = T / TPI;
;     const int xcd_ = (int)blockIdx.x & 7, j_ = x8 ? ((int)blockIdx.x >> 3) : (int)blockIdx.x, J_ = x8 ? ((int)gridDim.x >> 3) : (int)gridDim.x;
	v_cvt_pk_bf16_f32 v63, v204, v205
	v_cvt_pk_bf16_f32 v64, v206, v207
	v_cvt_pk_bf16_f32 v65, v208, v209
	v_cvt_pk_bf16_f32 v66, v210, v211
	v_cvt_pk_bf16_f32 v67, v212, v213
	v_cvt_pk_bf16_f32 v68, v214, v215
	v_cvt_pk_bf16_f32 v69, v216, v217
	v_cvt_pk_bf16_f32 v70, v218, v219
	v_cvt_pk_bf16_f32 v71, v220, v221
	v_cvt_pk_bf16_f32 v72, v222, v223
	v_cvt_pk_bf16_f32 v73, v224, v225
	v_cvt_pk_bf16_f32 v74, v226, v227
	v_cvt_pk_bf16_f32 v75, v228, v229
	v_cvt_pk_bf16_f32 v76, v230, v231
	v_cvt_pk_bf16_f32 v77, v232, v233
	v_cvt_pk_bf16_f32 v78, v234, v235
	global_load_dword v204, v[6:7], off
	global_load_dword v205, v[6:7], off offset:1024
	global_load_dword v206, v[6:7], off offset:2048
	global_load_dword v207, v[6:7], off offset:3072
	v_add_co_u32_e32 v4, vcc, s0, v2
	s_mov_b32 s0, 0xa000
	s_nop 0
	v_addc_co_u32_e32 v5, vcc, 0, v3, vcc
	v_add_co_u32_e32 v6, vcc, s0, v2
	s_mov_b32 s0, 0xb000
	s_nop 0
	v_addc_co_u32_e32 v7, vcc, 0, v3, vcc
	global_load_dword v208, v[6:7], off offset:-4096
	global_load_dword v209, v[4:5], off offset:1024
	global_load_dword v210, v[4:5], off offset:2048
	s_nop 0
	global_load_dword v211, v[4:5], off offset:3072
	global_load_dword v212, v[6:7], off
	global_load_dword v213, v[6:7], off offset:1024
	global_load_dword v214, v[6:7], off offset:2048
	global_load_dword v215, v[6:7], off offset:3072
	v_add_co_u32_e32 v4, vcc, s0, v2
	s_mov_b32 s0, 0xc000
	s_nop 0
	v_addc_co_u32_e32 v5, vcc, 0, v3, vcc
	v_add_co_u32_e32 v6, vcc, s0, v2
	s_mov_b32 s0, 0xd000
	s_nop 0
	v_addc_co_u32_e32 v7, vcc, 0, v3, vcc
	global_load_dword v216, v[6:7], off offset:-4096
	global_load_dword v217, v[4:5], off offset:1024
	global_load_dword v218, v[4:5], off offset:2048
	s_nop 0
	global_load_dword v219, v[4:5], off offset:3072
	global_load_dword v220, v[6:7], off
	global_load_dword v221, v[6:7], off offset:1024
	global_load_dword v222, v[6:7], off offset:2048
	global_load_dword v223, v[6:7], off offset:3072
	v_add_co_u32_e32 v4, vcc, s0, v2
	s_mov_b32 s0, 0xe000
	s_nop 0
	v_addc_co_u32_e32 v5, vcc, 0, v3, vcc
	v_add_co_u32_e32 v6, vcc, s0, v2
	s_mov_b32 s0, 0xf000
	s_nop 0
	v_addc_co_u32_e32 v7, vcc, 0, v3, vcc
	global_load_dword v224, v[6:7], off offset:-4096
	global_load_dword v225, v[4:5], off offset:1024
	global_load_dword v226, v[4:5], off offset:2048
	s_nop 0
	global_load_dword v227, v[4:5], off offset:3072
	global_load_dword v228, v[6:7], off
	global_load_dword v229, v[6:7], off offset:1024
	global_load_dword v230, v[6:7], off offset:2048
	global_load_dword v231, v[6:7], off offset:3072
	v_add_co_u32_e32 v4, vcc, s0, v2
	s_nop 1
	v_addc_co_u32_e32 v5, vcc, 0, v3, vcc
	global_load_dword v232, v[4:5], off
	global_load_dword v233, v[4:5], off offset:1024
	global_load_dword v234, v[4:5], off offset:2048
	s_nop 0
	global_load_dword v235, v[4:5], off offset:3072
	s_waitcnt vmcnt(0)
	v_cvt_pk_bf16_f32 v79, v204, v205
	v_cvt_pk_bf16_f32 v80, v206, v207
	v_cvt_pk_bf16_f32 v81, v208, v209
	v_cvt_pk_bf16_f32 v82, v210, v211
	v_cvt_pk_bf16_f32 v83, v212, v213
	v_cvt_pk_bf16_f32 v84, v214, v215
	v_cvt_pk_bf16_f32 v85, v216, v217
	v_cvt_pk_bf16_f32 v86, v218, v219
	v_cvt_pk_bf16_f32 v87, v220, v221
	v_cvt_pk_bf16_f32 v88, v222, v223
	v_cvt_pk_bf16_f32 v89, v224, v225
	v_cvt_pk_bf16_f32 v90, v226, v227
	v_cvt_pk_bf16_f32 v91, v228, v229
	v_cvt_pk_bf16_f32 v92, v230, v231
	v_cvt_pk_bf16_f32 v3, v232, v233
	v_cvt_pk_bf16_f32 v93, v234, v235
	v_and_b32_e32 v2, 0x7f, v10
	v_lshlrev_b32_e32 v140, 2, v2
	v_lshl_add_u64 v[4:5], s[6:7], 0, v[140:141]
	v_lshlrev_b32_e32 v140, 1, v0
	v_lshl_add_u64 v[6:7], s[30:31], 0, v[140:141]
	s_mov_b64 s[6:7], 0x1b350000
	v_lshlrev_b32_e32 v140, 2, v94
	v_add_u32_e32 v10, 0x600, v10
	v_lshl_add_u64 v[6:7], v[6:7], 0, s[6:7]
	v_lshl_add_u64 v[8:9], s[30:31], 0, v[140:141]
	s_mov_b64 s[6:7], 0x1c360000
	v_ashrrev_i32_e32 v104, 7, v10
	v_lshlrev_b32_e32 v10, 1, v11
	v_mov_b32_e32 v11, v141
	v_lshl_add_u64 v[8:9], v[8:9], 0, s[6:7]
	v_lshl_add_u64 v[12:13], s[30:31], 0, v[10:11]
	s_mov_b64 s[6:7], 0x142e0000
	v_cmp_lt_u32_e64 s[10:11], 31, v2
	v_cmp_gt_u32_e64 s[12:13], 64, v2
	v_and_b32_e32 v105, 15, v104
	v_lshl_add_u64 v[12:13], v[12:13], 0, s[6:7]
	s_branch .LBB0_490

; __device__ __forceinline__ int ltid() { int t = threadIdx.x; asm volatile("" : "+v"(t)); return t; }
; template <bool SRC_F32, bool DST_F32, bool HAS_H>
; __device__ __forceinline__ void phase_rowpass(const void* xp, const void* xs, const bf16* Y, float coef, const float* gpost, const float* gpre, void* xdst, bf16* H) {
;     const int tid = ltid(), lane = tid & 63, wave = tid >> 6;
;     const int gw = blockIdx.x * NWAVES + wave, NGW = gridDim.x * NWAVES;
;     f32x4 y[4], x[4], nxf[4]; u32x2 ny[4], nxb[4];
;     ...
;     if (gw < MR) RP_LOAD(gw);
;     for (int m = gw; m < MR; m += NGW) {
; #pragma unroll
;         for (int j = 0; j < 4; ++j) { y[j] = (f32x4){bflo(ny[j].x), bfhi(ny[j].x), bflo(ny[j].y), bfhi(ny[j].y)};
;             x[j] = SRC_F32 ? nxf[j] : (f32x4){bflo(nxb[j].x), bfhi(nxb[j].x), bflo(nxb[j].y), bfhi(nxb[j].y)}; }
;         if (m + NGW < MR) RP_LOAD(m + NGW);
;         float s = 0.f;
; #pragma unroll
;         for (int j = 0; j < 4; ++j) s += (y[j].x * y[j].x + y[j].y * y[j].y) + (y[j].z * y[j].z + y[j].w * y[j].w);
;         const float rstd = rsqrtf(wave_sum(s) * (1.f / D) + RMS_EPS) * coef;
;         float s2 = 0.f;
; #pragma unroll
;         for (int j = 0; j < 4; ++j) { const f32x4 gg = *((const f32x4*)gpost + lane + 64 * j);
;             x[j].x += y[j].x * rstd * gg.x; x[j].y += y[j].y * rstd * gg.y; x[j].z += y[j].z * rstd * gg.z; x[j].w += y[j].w * rstd * gg.w;
.LBB0_1144:
	s_or_b64 exec, exec, s[4:5]
	v_readlane_b32 s4, v253, 2
	v_readlane_b32 s5, v253, 3
	s_waitcnt lgkmcnt(0)
	s_barrier
	s_load_dwordx4 s[12:15], s[4:5], 0xe0
	s_nop 0
	s_load_dwordx2 s[4:5], s[4:5], 0x40
	v_readlane_b32 s8, v255, 2
	v_readlane_b32 s10, v254, 58
	v_readlane_b32 s9, v255, 3
	s_waitcnt lgkmcnt(0)
	s_add_u32 s6, s14, 0x142e0000
	s_addc_u32 s7, s15, 0
	s_add_u32 s4, s4, s8
	v_readlane_b32 s11, v254, 59
	s_addc_u32 s5, s5, s9
	s_mov_b64 s[8:9], -1
	s_and_b64 vcc, exec, s[10:11]
	s_cbranch_vccz .LBB0_1151
	v_mov_b32_e32 v1, v172
	v_readlane_b32 s0, v253, 6
	v_ashrrev_i32_e32 v2, 6, v1
	s_nop 0
	v_add_u32_e32 v0, s0, v2
	v_cmp_gt_i32_e32 vcc, s93, v0
	s_and_saveexec_b64 s[8:9], vcc
	s_cbranch_execz .LBB0_1150
	v_and_b32_e32 v8, 63, v1
	v_ashrrev_i32_e32 v1, 31, v0
	v_lshlrev_b64 v[4:5], 11, v[0:1]
	v_lshl_add_u64 v[6:7], s[6:7], 0, v[4:5]
	v_lshlrev_b32_e32 v140, 3, v8
	v_lshl_add_u64 v[6:7], v[6:7], 0, v[140:141]
	global_load_dwordx2 v[38:39], v[6:7], off
	global_load_dwordx2 v[34:35], v[6:7], off offset:512
	global_load_dwordx2 v[28:29], v[6:7], off offset:1536
	global_load_dwordx2 v[32:33], v[6:7], off offset:1024
	v_lshl_add_u64 v[6:7], s[12:13], 0, v[4:5]
	v_lshl_add_u64 v[6:7], v[6:7], 0, v[140:141]
	global_load_dwordx2 v[30:31], v[6:7], off offset:1536
	global_load_dwordx2 v[36:37], v[6:7], off offset:1024
	global_load_dwordx2 v[40:41], v[6:7], off offset:512
	global_load_dwordx2 v[42:43], v[6:7], off
	v_readlane_b32 s0, v254, 21
	v_mov_b32_e32 v3, v141
	s_mov_b64 s[10:11], 0x3000
	v_add_u32_e32 v6, s0, v2
	v_lshlrev_b32_e32 v2, 4, v8
	v_ashrrev_i32_e32 v7, 31, v6
	v_lshl_add_u64 v[8:9], s[4:5], 0, v[2:3]
	v_lshl_add_u64 v[2:3], s[14:15], 0, v[4:5]
	v_lshlrev_b64 v[10:11], 11, v[6:7]
	v_lshl_add_u64 v[4:5], v[8:9], 0, s[10:11]
	s_mov_b64 s[10:11], 0x4000
	s_mov_b64 s[16:17], 0
	v_lshl_add_u64 v[6:7], v[8:9], 0, s[10:11]
	v_lshl_add_u64 v[8:9], s[14:15], 0, v[10:11]
	v_lshl_add_u64 v[10:11], s[12:13], 0, v[10:11]
	s_waitcnt vmcnt(7)
	v_mov_b64_e32 v[18:19], v[38:39]
	s_waitcnt vmcnt(6)
	v_mov_b64_e32 v[16:17], v[34:35]
	s_waitcnt vmcnt(5)
	v_mov_b64_e32 v[12:13], v[28:29]
	s_waitcnt vmcnt(4)
	v_mov_b64_e32 v[14:15], v[32:33]
	s_waitcnt vmcnt(3)
	v_mov_b64_e32 v[20:21], v[30:31]
	s_waitcnt vmcnt(2)
	v_mov_b64_e32 v[22:23], v[36:37]
	s_waitcnt vmcnt(1)
	v_mov_b64_e32 v[24:25], v[40:41]
	s_waitcnt vmcnt(0)
	v_mov_b64_e32 v[26:27], v[42:43]
	global_load_dwordx4 v[200:203], v[4:5], off
	global_load_dwordx4 v[204:207], v[4:5], off offset:1024
	global_load_dwordx4 v[208:211], v[4:5], off offset:2048
	global_load_dwordx4 v[212:215], v[4:5], off offset:3072
	global_load_dwordx4 v[216:219], v[6:7], off
	global_load_dwordx4 v[220:223], v[6:7], off offset:1024
	global_load_dwordx4 v[224:227], v[6:7], off offset:2048
	global_load_dwordx4 v[228:231], v[6:7], off offset:3072
	s_waitcnt vmcnt(0)
	s_branch .LBB0_1148
.LBB0_1147:
	s_or_b64 exec, exec, s[10:11]
	v_and_b32_e32 v57, 0xffff0000, v38
	v_and_b32_e32 v61, 0xffff0000, v39
	v_lshlrev_b32_e32 v56, 16, v38
	v_lshlrev_b32_e32 v60, 16, v39
	v_lshlrev_b32_e32 v54, 16, v40
	v_and_b32_e32 v55, 0xffff0000, v40
	v_lshlrev_b32_e32 v48, 16, v41
	v_and_b32_e32 v49, 0xffff0000, v41
	v_mov_b32_e32 v40, v57
	v_mov_b32_e32 v41, v61
	v_lshlrev_b32_e32 v58, 16, v42
	v_and_b32_e32 v59, 0xffff0000, v42
	v_lshlrev_b32_e32 v62, 16, v43
	v_and_b32_e32 v63, 0xffff0000, v43
	v_lshlrev_b32_e32 v53, 16, v35
	v_lshlrev_b32_e32 v52, 16, v34
	v_and_b32_e32 v51, 0xffff0000, v35
	v_and_b32_e32 v50, 0xffff0000, v34
	v_lshlrev_b32_e32 v42, 16, v33
	v_and_b32_e32 v43, 0xffff0000, v33
	v_lshlrev_b32_e32 v44, 16, v32
	v_and_b32_e32 v45, 0xffff0000, v32
	v_lshlrev_b32_e32 v34, 16, v28
	v_and_b32_e32 v35, 0xffff0000, v28
	v_lshlrev_b32_e32 v32, 16, v29
	v_and_b32_e32 v33, 0xffff0000, v29
	v_mov_b32_e32 v28, v56
	v_mov_b32_e32 v29, v60
	v_pk_mul_f32 v[40:41], v[40:41], v[40:41]
	v_pk_mul_f32 v[66:67], v[34:35], v[34:35]
	v_pk_fma_f32 v[28:29], v[28:29], v[28:29], v[40:41]
	v_pk_mul_f32 v[40:41], v[50:51], v[50:51]
	v_pk_add_f32 v[28:29], v[28:29], v[28:29] op_sel_hi:[0,1]
	v_mul_f32_e32 v28, v42, v42
	v_pk_fma_f32 v[40:41], v[52:53], v[52:53], v[40:41]
	v_pk_fma_f32 v[64:65], v[42:43], v[42:43], v[28:29] op_sel_hi:[1,1,0]
	v_mul_f32_e32 v28, v44, v44
	v_pk_add_f32 v[40:41], v[40:41], v[40:41] op_sel_hi:[0,1]
	v_pk_mul_f32 v[68:69], v[32:33], v[32:33]
	v_pk_fma_f32 v[70:71], v[44:45], v[44:45], v[28:29] op_sel_hi:[1,1,0]
	v_mov_b32_e32 v64, v67
	v_mov_b32_e32 v70, v66
	v_mov_b32_e32 v40, v68
	v_mov_b32_e32 v28, v69
	v_pk_add_f32 v[64:65], v[70:71], v[64:65]
	v_pk_add_f32 v[28:29], v[40:41], v[28:29]
	v_lshlrev_b32_e32 v46, 16, v36
	v_pk_add_f32 v[28:29], v[64:65], v[28:29]
	v_add_f32_e32 v1, v28, v29
	v_and_b32_e32 v47, 0xffff0000, v36
	v_lshlrev_b32_e32 v38, 16, v37
	v_add_f32_dpp v1, v1, v1 quad_perm:[1,0,3,2] row_mask:0xf bank_mask:0xf bound_ctrl:1
	v_and_b32_e32 v39, 0xffff0000, v37
	v_lshlrev_b32_e32 v36, 16, v30
	v_add_f32_dpp v1, v1, v1 quad_perm:[2,3,0,1] row_mask:0xf bank_mask:0xf bound_ctrl:1
	v_and_b32_e32 v37, 0xffff0000, v30
	v_lshlrev_b32_e32 v30, 16, v31
	v_add_f32_dpp v1, v1, v1 row_half_mirror row_mask:0xf bank_mask:0xf bound_ctrl:1
	v_and_b32_e32 v31, 0xffff0000, v31
	v_lshl_add_u64 v[8:9], v[8:9], 0, s[82:83]
	v_add_f32_dpp v1, v1, v1 row_mirror row_mask:0xf bank_mask:0xf bound_ctrl:1
	v_lshl_add_u64 v[10:11], v[10:11], 0, s[82:83]
	v_readlane_b32 s0, v1, 16
	v_readlane_b32 s18, v1, 48
	v_readlane_b32 s10, v1, 0
	v_readlane_b32 s11, v1, 32
	v_mov_b32_e32 v28, s0
	v_mov_b32_e32 v29, s18
	v_pk_add_f32 v[28:29], s[10:11], v[28:29]
	s_mov_b32 s10, 0x18360000
	v_add_f32_e32 v1, v28, v29
	v_fmamk_f32 v1, v1, 0x3a800000, v177
	v_cmp_gt_f32_e32 vcc, s65, v1
	v_mul_f32_e32 v28, 0x4b800000, v1
	s_nop 0
	v_cndmask_b32_e32 v1, v1, v28, vcc
	v_rsq_f32_e32 v1, v1
	s_nop 0
	v_mul_f32_e32 v28, 0x45800000, v1
	v_cndmask_b32_e32 v40, v1, v28, vcc
	v_pk_mul_f32 v[56:57], v[40:41], v[56:57] op_sel_hi:[0,1]
	v_lshl_add_u64 v[28:29], v[2:3], 0, v[140:141]
	v_pk_mul_f32 v[44:45], v[40:41], v[44:45] op_sel_hi:[0,1]
	v_pk_mul_f32 v[42:43], v[40:41], v[42:43] op_sel_hi:[0,1]
	v_pk_mul_f32 v[34:35], v[40:41], v[34:35] op_sel_hi:[0,1]
	v_pk_mul_f32 v[32:33], v[40:41], v[32:33] op_sel_hi:[0,1]
	v_lshl_add_u64 v[2:3], v[2:3], 0, s[82:83]
	s_waitcnt vmcnt(0)
; __device__ __forceinline__ unsigned pk2(float lo, float hi) { f32x2_t v = {lo, hi}; bf16x2_t b = __builtin_convertvector(v, bf16x2_t); return __builtin_bit_cast(unsigned, b); }
; template <bool SRC_F32, bool DST_F32, bool HAS_H>
; __device__ __forceinline__ void phase_rowpass(const void* xp, const void* xs, const bf16* Y, float coef, const float* gpost, const float* gpre, void* xdst, bf16* H) {
;     ...
;         for (int j = 0; j < 4; ++j) { const f32x4 gg = *((const f32x4*)gpost + lane + 64 * j);
;             x[j].x += y[j].x * rstd * gg.x; x[j].y += y[j].y * rstd * gg.y; x[j].z += y[j].z * rstd * gg.z; x[j].w += y[j].w * rstd * gg.w;
;             s2 += (x[j].x * x[j].x + x[j].y * x[j].y) + (x[j].z * x[j].z + x[j].w * x[j].w);
;             if (DST_F32) *((f32x4*)((float*)xdst + (size_t)m * D) + lane + 64 * j) = x[j];
;             else { u32x2 o; o.x = pk2(x[j].x, x[j].y); o.y = pk2(x[j].z, x[j].w); *((u32x2*)((bf16*)xdst + (size_t)m * D) + lane + 64 * j) = o; } }
;         if (HAS_H) {
;             const float r2 = rsqrtf(wave_sum(s2) * (1.f / D) + RMS_EPS);
; #pragma unroll
;             for (int j = 0; j < 4; ++j) { const f32x4 gg = *((const f32x4*)gpre + lane + 64 * j); u32x2 o; o.x = pk2(x[j].x * r2 * gg.x, x[j].y * r2 * gg.y); o.y = pk2(x[j].z * r2 * gg.z, x[j].w * r2 * gg.w);
;                 *((u32x2*)(H + (size_t)m * D) + lane + 64 * j) = o; }
	v_pk_fma_f32 v[58:59], v[200:201], v[56:57], v[58:59]
	v_pk_mul_f32 v[56:57], v[40:41], v[60:61] op_sel_hi:[0,1]
	v_pk_fma_f32 v[56:57], v[202:203], v[56:57], v[62:63]
	v_mov_b32_e32 v62, v59
	v_mov_b32_e32 v63, v57
	v_mov_b32_e32 v60, v58
	v_mov_b32_e32 v61, v56
	v_pk_mul_f32 v[62:63], v[62:63], v[62:63]
	v_add_co_u32_e32 v64, vcc, s10, v28
	v_pk_fma_f32 v[60:61], v[60:61], v[60:61], v[62:63]
	v_cvt_pk_bf16_f32 v62, v58, v59
	v_cvt_pk_bf16_f32 v63, v56, v57
	v_addc_co_u32_e32 v65, vcc, 0, v29, vcc
	global_store_dwordx2 v[64:65], v[62:63], off
	v_mov_b32_e32 v62, v52
	v_mov_b32_e32 v63, v50
	v_mov_b32_e32 v50, v53
	v_pk_mul_f32 v[62:63], v[40:41], v[62:63] op_sel_hi:[0,1]
	v_pk_mul_f32 v[50:51], v[40:41], v[50:51] op_sel_hi:[0,1]
	v_pk_add_f32 v[60:61], v[60:61], v[60:61] op_sel_hi:[0,1]
	v_pk_fma_f32 v[54:55], v[204:205], v[62:63], v[54:55]
	v_pk_fma_f32 v[48:49], v[206:207], v[50:51], v[48:49]
	v_mov_b32_e32 v52, v55
	v_mov_b32_e32 v53, v49
	v_mov_b32_e32 v50, v54
	v_mov_b32_e32 v51, v48
	v_pk_mul_f32 v[52:53], v[52:53], v[52:53]
	s_nop 0
	v_pk_fma_f32 v[50:51], v[50:51], v[50:51], v[52:53]
	s_nop 0
	v_pk_add_f32 v[62:63], v[50:51], v[50:51] op_sel_hi:[0,1]
	v_cvt_pk_bf16_f32 v50, v54, v55
	v_cvt_pk_bf16_f32 v51, v48, v49
	global_store_dwordx2 v[64:65], v[50:51], off offset:512
	v_pk_fma_f32 v[44:45], v[208:209], v[44:45], v[46:47]
	v_pk_fma_f32 v[38:39], v[210:211], v[42:43], v[38:39]
	v_cvt_pk_bf16_f32 v50, v44, v45
	v_cvt_pk_bf16_f32 v51, v38, v39
	global_store_dwordx2 v[64:65], v[50:51], off offset:1024
	v_mul_f32_e32 v42, v44, v44
	v_pk_fma_f32 v[42:43], v[44:45], v[44:45], v[42:43] op_sel_hi:[1,1,0]
	v_pk_fma_f32 v[34:35], v[212:213], v[34:35], v[36:37]
	v_mul_f32_e32 v42, v38, v38
	v_pk_fma_f32 v[30:31], v[214:215], v[32:33], v[30:31]
	v_pk_fma_f32 v[46:47], v[38:39], v[38:39], v[42:43] op_sel_hi:[1,1,0]
	v_pk_mul_f32 v[32:33], v[34:35], v[34:35]
	v_pk_mul_f32 v[36:37], v[30:31], v[30:31]
	v_mov_b32_e32 v42, v32
	v_mov_b32_e32 v46, v33
	v_mov_b32_e32 v60, v36
	v_mov_b32_e32 v62, v37
	v_pk_add_f32 v[32:33], v[42:43], v[46:47]
	v_pk_add_f32 v[36:37], v[60:61], v[62:63]
	s_nop 0
	v_pk_add_f32 v[32:33], v[32:33], v[36:37]
	s_nop 0
	v_add_f32_e32 v1, v32, v33
	v_cvt_pk_bf16_f32 v32, v34, v35
	v_cvt_pk_bf16_f32 v33, v30, v31
	global_store_dwordx2 v[64:65], v[32:33], off offset:1536
	v_add_f32_dpp v1, v1, v1 quad_perm:[1,0,3,2] row_mask:0xf bank_mask:0xf bound_ctrl:1
	s_nop 1
	v_add_f32_dpp v1, v1, v1 quad_perm:[2,3,0,1] row_mask:0xf bank_mask:0xf bound_ctrl:1
	s_nop 1
	v_add_f32_dpp v1, v1, v1 row_half_mirror row_mask:0xf bank_mask:0xf bound_ctrl:1
	s_nop 1
	v_add_f32_dpp v1, v1, v1 row_mirror row_mask:0xf bank_mask:0xf bound_ctrl:1
	s_nop 0
	v_readlane_b32 s0, v1, 16
	v_readlane_b32 s18, v1, 48
	v_readlane_b32 s10, v1, 0
	v_readlane_b32 s11, v1, 32
	v_mov_b32_e32 v32, s0
	v_mov_b32_e32 v33, s18
	v_pk_add_f32 v[32:33], s[10:11], v[32:33]
	s_mov_b32 s0, 0x5100000
	v_add_f32_e32 v1, v32, v33
	v_fmamk_f32 v1, v1, 0x3a800000, v177
	v_cmp_gt_f32_e32 vcc, s65, v1
	v_mul_f32_e32 v32, 0x4b800000, v1
	s_nop 0
	v_cndmask_b32_e32 v1, v1, v32, vcc
	v_rsq_f32_e32 v1, v1
	s_nop 0
	v_mul_f32_e32 v32, 0x45800000, v1
	v_cndmask_b32_e32 v32, v1, v32, vcc
	v_pk_mul_f32 v[36:37], v[58:59], v[32:33] op_sel_hi:[1,0]
	v_add_co_u32_e32 v28, vcc, s0, v28
	v_pk_mul_f32 v[38:39], v[38:39], v[32:33] op_sel_hi:[1,0]
	s_nop 0
	v_addc_co_u32_e32 v29, vcc, 0, v29, vcc
	v_pk_mul_f32 v[34:35], v[34:35], v[32:33] op_sel_hi:[1,0]
	v_pk_mul_f32 v[30:31], v[30:31], v[32:33] op_sel_hi:[1,0]
	v_pk_mul_f32 v[36:37], v[216:217], v[36:37]
	v_pk_mul_f32 v[40:41], v[56:57], v[32:33] op_sel_hi:[1,0]
	v_cvt_pk_bf16_f32 v36, v36, v37
	v_pk_mul_f32 v[40:41], v[218:219], v[40:41]
	s_nop 0
	v_cvt_pk_bf16_f32 v37, v40, v41
	global_store_dwordx2 v[28:29], v[36:37], off
	v_pk_mul_f32 v[36:37], v[54:55], v[32:33] op_sel_hi:[1,0]
	v_pk_mul_f32 v[36:37], v[220:221], v[36:37]
	v_pk_mul_f32 v[40:41], v[48:49], v[32:33] op_sel_hi:[1,0]
	v_cvt_pk_bf16_f32 v36, v36, v37
	v_pk_mul_f32 v[40:41], v[222:223], v[40:41]
	s_nop 0
	v_cvt_pk_bf16_f32 v37, v40, v41
	global_store_dwordx2 v[28:29], v[36:37], off offset:512
	v_pk_mul_f32 v[36:37], v[44:45], v[32:33] op_sel_hi:[1,0]
	v_mov_b64_e32 v[32:33], v[14:15]
	v_pk_mul_f32 v[36:37], v[224:225], v[36:37]
	v_pk_mul_f32 v[38:39], v[226:227], v[38:39]
	v_cvt_pk_bf16_f32 v36, v36, v37
	v_cvt_pk_bf16_f32 v37, v38, v39
	global_store_dwordx2 v[28:29], v[36:37], off offset:1024
	v_mov_b64_e32 v[40:41], v[24:25]
	v_mov_b64_e32 v[42:43], v[26:27]
	v_pk_mul_f32 v[34:35], v[228:229], v[34:35]
	v_pk_mul_f32 v[30:31], v[230:231], v[30:31]
	v_cvt_pk_bf16_f32 v34, v34, v35
	v_cvt_pk_bf16_f32 v35, v30, v31
	global_store_dwordx2 v[28:29], v[34:35], off offset:1536
	v_mov_b64_e32 v[28:29], v[12:13]
	v_mov_b64_e32 v[34:35], v[16:17]
	v_mov_b64_e32 v[38:39], v[18:19]
	v_mov_b64_e32 v[30:31], v[20:21]
	v_mov_b64_e32 v[36:37], v[22:23]
	s_andn2_b64 exec, exec, s[16:17]
	s_cbranch_execz .LBB0_1150

; __device__ __forceinline__ int ltid() { int t = threadIdx.x; asm volatile("" : "+v"(t)); return t; }
; template <bool SRC_F32, bool DST_F32, bool HAS_H>
; __device__ __forceinline__ void phase_rowpass(const void* xp, const void* xs, const bf16* Y, float coef, const float* gpost, const float* gpre, void* xdst, bf16* H) {
;     const int tid = ltid(), lane = tid & 63, wave = tid >> 6;
;     const int gw = blockIdx.x * NWAVES + wave, NGW = gridDim.x * NWAVES;
;     f32x4 y[4], x[4], nxf[4]; u32x2 ny[4], nxb[4];
;     ...
;     if (gw < MR) RP_LOAD(gw);
;     for (int m = gw; m < MR; m += NGW) {
; #pragma unroll
;         for (int j = 0; j < 4; ++j) { y[j] = (f32x4){bflo(ny[j].x), bfhi(ny[j].x), bflo(ny[j].y), bfhi(ny[j].y)};
;             x[j] = SRC_F32 ? nxf[j] : (f32x4){bflo(nxb[j].x), bfhi(nxb[j].x), bflo(nxb[j].y), bfhi(nxb[j].y)}; }
;         if (m + NGW < MR) RP_LOAD(m + NGW);
;         float s = 0.f;
; #pragma unroll
;         for (int j = 0; j < 4; ++j) s += (y[j].x * y[j].x + y[j].y * y[j].y) + (y[j].z * y[j].z + y[j].w * y[j].w);
;         const float rstd = rsqrtf(wave_sum(s) * (1.f / D) + RMS_EPS) * coef;
;         float s2 = 0.f;
; #pragma unroll
;         for (int j = 0; j < 4; ++j) { const f32x4 gg = *((const f32x4*)gpost + lane + 64 * j);
;             x[j].x += y[j].x * rstd * gg.x; x[j].y += y[j].y * rstd * gg.y; x[j].z += y[j].z * rstd * gg.z; x[j].w += y[j].w * rstd * gg.w;
.LBB0_1151:
	s_andn2_b64 vcc, exec, s[8:9]
	s_cbranch_vccnz .LBB0_1158
	v_mov_b32_e32 v0, v172
	v_readlane_b32 s0, v253, 6
	v_ashrrev_i32_e32 v8, 6, v0
	s_nop 0
	v_add_u32_e32 v4, s0, v8
	v_cmp_gt_i32_e32 vcc, s93, v4
	s_and_saveexec_b64 s[8:9], vcc
	s_cbranch_execz .LBB0_1157
	v_ashrrev_i32_e32 v5, 31, v4
	v_and_b32_e32 v14, 63, v0
	v_lshlrev_b64 v[10:11], 11, v[4:5]
	v_lshl_add_u64 v[0:1], s[6:7], 0, v[10:11]
	v_lshlrev_b32_e32 v140, 3, v14
	v_lshl_add_u64 v[6:7], s[12:13], 0, v[10:11]
	v_lshl_add_u64 v[2:3], v[0:1], 0, v[140:141]
	v_lshl_add_u64 v[12:13], v[6:7], 0, v[140:141]
	global_load_dwordx2 v[40:41], v[2:3], off
	global_load_dwordx2 v[36:37], v[2:3], off offset:512
	global_load_dwordx2 v[0:1], v[2:3], off offset:1536
	global_load_dwordx2 v[34:35], v[2:3], off offset:1024
	s_nop 0
	global_load_dwordx2 v[2:3], v[12:13], off offset:1536
	global_load_dwordx2 v[38:39], v[12:13], off offset:1024
	global_load_dwordx2 v[42:43], v[12:13], off offset:512
	global_load_dwordx2 v[44:45], v[12:13], off
	v_readlane_b32 s0, v254, 21
	v_mov_b32_e32 v9, v141
	s_mov_b64 s[6:7], 0
	v_add_u32_e32 v12, s0, v8
	v_lshlrev_b32_e32 v8, 4, v14
	v_ashrrev_i32_e32 v13, 31, v12
	v_lshl_add_u64 v[14:15], s[4:5], 0, v[8:9]
	s_mov_b64 s[4:5], 0x3000
	v_lshl_add_u64 v[8:9], s[14:15], 0, v[10:11]
	v_lshlrev_b64 v[16:17], 11, v[12:13]
	v_lshl_add_u64 v[10:11], v[14:15], 0, s[4:5]
	s_mov_b64 s[4:5], 0x4000
	v_lshl_add_u64 v[12:13], v[14:15], 0, s[4:5]
	v_lshl_add_u64 v[14:15], s[14:15], 0, v[16:17]
	v_lshl_add_u64 v[16:17], s[12:13], 0, v[16:17]
	s_waitcnt vmcnt(7)
	v_mov_b64_e32 v[24:25], v[40:41]
	s_waitcnt vmcnt(6)
	v_mov_b64_e32 v[22:23], v[36:37]
	s_waitcnt vmcnt(5)
	v_mov_b64_e32 v[18:19], v[0:1]
	s_waitcnt vmcnt(4)
	v_mov_b64_e32 v[20:21], v[34:35]
	s_waitcnt vmcnt(3)
	v_mov_b64_e32 v[26:27], v[2:3]
	s_waitcnt vmcnt(2)
	v_mov_b64_e32 v[28:29], v[38:39]
	s_waitcnt vmcnt(1)
	v_mov_b64_e32 v[30:31], v[42:43]
	s_waitcnt vmcnt(0)
	v_mov_b64_e32 v[32:33], v[44:45]
	global_load_dwordx4 v[200:203], v[10:11], off
	global_load_dwordx4 v[204:207], v[10:11], off offset:1024
	global_load_dwordx4 v[208:211], v[10:11], off offset:2048
	global_load_dwordx4 v[212:215], v[10:11], off offset:3072
	global_load_dwordx4 v[216:219], v[12:13], off
	global_load_dwordx4 v[220:223], v[12:13], off offset:1024
	global_load_dwordx4 v[224:227], v[12:13], off offset:2048
	global_load_dwordx4 v[228:231], v[12:13], off offset:3072
	s_waitcnt vmcnt(0)
	s_branch .LBB0_1155
.LBB0_1154:
	s_or_b64 exec, exec, s[4:5]
	v_and_b32_e32 v67, 0xffff0000, v40
	v_and_b32_e32 v65, 0xffff0000, v41
	v_lshlrev_b32_e32 v66, 16, v40
	v_lshlrev_b32_e32 v64, 16, v41
	v_lshlrev_b32_e32 v59, 16, v37
	v_lshlrev_b32_e32 v58, 16, v36
	v_and_b32_e32 v57, 0xffff0000, v37
	v_and_b32_e32 v56, 0xffff0000, v36
	v_lshlrev_b32_e32 v60, 16, v42
	v_and_b32_e32 v61, 0xffff0000, v42
	v_lshlrev_b32_e32 v54, 16, v43
	v_and_b32_e32 v55, 0xffff0000, v43
	v_lshlrev_b32_e32 v42, 16, v2
	v_and_b32_e32 v43, 0xffff0000, v2
	v_lshlrev_b32_e32 v36, 16, v3
	v_and_b32_e32 v37, 0xffff0000, v3
	v_mov_b32_e32 v2, v67
	v_mov_b32_e32 v3, v65
	v_lshlrev_b32_e32 v68, 16, v44
	v_and_b32_e32 v69, 0xffff0000, v44
	v_lshlrev_b32_e32 v62, 16, v45
	v_and_b32_e32 v63, 0xffff0000, v45
	v_lshlrev_b32_e32 v52, 16, v38
	v_and_b32_e32 v53, 0xffff0000, v38
	v_lshlrev_b32_e32 v44, 16, v39
	v_and_b32_e32 v45, 0xffff0000, v39
	v_lshlrev_b32_e32 v40, 16, v0
	v_and_b32_e32 v41, 0xffff0000, v0
	v_lshlrev_b32_e32 v38, 16, v1
	v_and_b32_e32 v39, 0xffff0000, v1
	v_mov_b32_e32 v0, v66
	v_mov_b32_e32 v1, v64
	v_pk_mul_f32 v[2:3], v[2:3], v[2:3]
	v_lshlrev_b32_e32 v48, 16, v35
	v_pk_fma_f32 v[0:1], v[0:1], v[0:1], v[2:3]
	v_and_b32_e32 v49, 0xffff0000, v35
	v_pk_add_f32 v[0:1], v[0:1], v[0:1] op_sel_hi:[0,1]
	v_lshlrev_b32_e32 v50, 16, v34
	v_pk_mul_f32 v[2:3], v[56:57], v[56:57]
	v_mul_f32_e32 v0, v48, v48
	v_and_b32_e32 v51, 0xffff0000, v34
	v_pk_fma_f32 v[2:3], v[58:59], v[58:59], v[2:3]
	v_pk_fma_f32 v[34:35], v[48:49], v[48:49], v[0:1] op_sel_hi:[1,1,0]
	v_mul_f32_e32 v0, v50, v50
	v_pk_add_f32 v[2:3], v[2:3], v[2:3] op_sel_hi:[0,1]
	v_pk_mul_f32 v[46:47], v[40:41], v[40:41]
	v_pk_mul_f32 v[70:71], v[38:39], v[38:39]
	v_pk_fma_f32 v[72:73], v[50:51], v[50:51], v[0:1] op_sel_hi:[1,1,0]
	v_mov_b32_e32 v34, v47
	v_mov_b32_e32 v72, v46
	v_mov_b32_e32 v2, v70
	v_mov_b32_e32 v0, v71
	v_pk_add_f32 v[34:35], v[72:73], v[34:35]
	v_pk_add_f32 v[0:1], v[2:3], v[0:1]
	v_lshl_add_u64 v[14:15], v[14:15], 0, s[82:83]
	v_pk_add_f32 v[0:1], v[34:35], v[0:1]
	v_lshl_add_u64 v[34:35], v[6:7], 0, v[140:141]
	v_add_f32_e32 v0, v0, v1
	v_lshl_add_u64 v[6:7], v[6:7], 0, s[82:83]
	v_lshl_add_u64 v[16:17], v[16:17], 0, s[82:83]
	v_add_f32_dpp v0, v0, v0 quad_perm:[1,0,3,2] row_mask:0xf bank_mask:0xf bound_ctrl:1
	s_nop 1
	v_add_f32_dpp v0, v0, v0 quad_perm:[2,3,0,1] row_mask:0xf bank_mask:0xf bound_ctrl:1
	s_nop 1
	v_add_f32_dpp v0, v0, v0 row_half_mirror row_mask:0xf bank_mask:0xf bound_ctrl:1
	s_nop 1
	v_add_f32_dpp v0, v0, v0 row_mirror row_mask:0xf bank_mask:0xf bound_ctrl:1
	s_nop 0
	v_readlane_b32 s0, v0, 16
	v_readlane_b32 s10, v0, 48
	v_readlane_b32 s4, v0, 0
	v_readlane_b32 s5, v0, 32
	v_mov_b32_e32 v0, s0
	v_mov_b32_e32 v1, s10
	v_pk_add_f32 v[0:1], s[4:5], v[0:1]
	s_nop 0
	v_add_f32_e32 v0, v0, v1
	v_fmamk_f32 v0, v0, 0x3a800000, v177
	v_cmp_gt_f32_e32 vcc, s65, v0
	v_mul_f32_e32 v1, 0x4b800000, v0
	s_nop 0
	v_cndmask_b32_e32 v0, v0, v1, vcc
	v_rsq_f32_e32 v0, v0
	s_nop 0
	v_mul_f32_e32 v1, 0x45800000, v0
	v_cndmask_b32_e32 v46, v0, v1, vcc
	v_pk_mul_f32 v[66:67], v[46:47], v[66:67] op_sel_hi:[0,1]
	v_pk_mul_f32 v[50:51], v[46:47], v[50:51] op_sel_hi:[0,1]
	v_pk_mul_f32 v[48:49], v[46:47], v[48:49] op_sel_hi:[0,1]
	v_pk_mul_f32 v[40:41], v[46:47], v[40:41] op_sel_hi:[0,1]
	v_pk_mul_f32 v[38:39], v[46:47], v[38:39] op_sel_hi:[0,1]
	s_waitcnt vmcnt(0)
; __device__ __forceinline__ unsigned pk2(float lo, float hi) { f32x2_t v = {lo, hi}; bf16x2_t b = __builtin_convertvector(v, bf16x2_t); return __builtin_bit_cast(unsigned, b); }
; template <bool SRC_F32, bool DST_F32, bool HAS_H>
; __device__ __forceinline__ void phase_rowpass(const void* xp, const void* xs, const bf16* Y, float coef, const float* gpost, const float* gpre, void* xdst, bf16* H) {
;     ...
;         for (int j = 0; j < 4; ++j) { const f32x4 gg = *((const f32x4*)gpost + lane + 64 * j);
;             x[j].x += y[j].x * rstd * gg.x; x[j].y += y[j].y * rstd * gg.y; x[j].z += y[j].z * rstd * gg.z; x[j].w += y[j].w * rstd * gg.w;
;             s2 += (x[j].x * x[j].x + x[j].y * x[j].y) + (x[j].z * x[j].z + x[j].w * x[j].w);
;             if (DST_F32) *((f32x4*)((float*)xdst + (size_t)m * D) + lane + 64 * j) = x[j];
;             else { u32x2 o; o.x = pk2(x[j].x, x[j].y); o.y = pk2(x[j].z, x[j].w); *((u32x2*)((bf16*)xdst + (size_t)m * D) + lane + 64 * j) = o; } }
;         if (HAS_H) {
;             const float r2 = rsqrtf(wave_sum(s2) * (1.f / D) + RMS_EPS);
; #pragma unroll
;             for (int j = 0; j < 4; ++j) { const f32x4 gg = *((const f32x4*)gpre + lane + 64 * j); u32x2 o; o.x = pk2(x[j].x * r2 * gg.x, x[j].y * r2 * gg.y); o.y = pk2(x[j].z * r2 * gg.z, x[j].w * r2 * gg.w);
;                 *((u32x2*)(H + (size_t)m * D) + lane + 64 * j) = o; }
	v_pk_fma_f32 v[66:67], v[200:201], v[66:67], v[68:69]
	v_pk_mul_f32 v[0:1], v[46:47], v[64:65] op_sel_hi:[0,1]
	v_pk_fma_f32 v[62:63], v[202:203], v[0:1], v[62:63]
	v_mov_b32_e32 v2, v67
	v_mov_b32_e32 v3, v63
	v_mov_b32_e32 v0, v66
	v_mov_b32_e32 v1, v62
	v_pk_mul_f32 v[2:3], v[2:3], v[2:3]
	v_mov_b32_e32 v68, v58
	v_pk_fma_f32 v[0:1], v[0:1], v[0:1], v[2:3]
	v_mov_b32_e32 v69, v56
	v_pk_add_f32 v[64:65], v[0:1], v[0:1] op_sel_hi:[0,1]
	v_cvt_pk_bf16_f32 v0, v66, v67
	v_cvt_pk_bf16_f32 v1, v62, v63
	global_store_dwordx2 v[34:35], v[0:1], off
	v_mov_b32_e32 v56, v59
	v_pk_mul_f32 v[68:69], v[46:47], v[68:69] op_sel_hi:[0,1]
	v_pk_mul_f32 v[56:57], v[46:47], v[56:57] op_sel_hi:[0,1]
	v_pk_fma_f32 v[0:1], v[204:205], v[68:69], v[60:61]
	v_pk_fma_f32 v[2:3], v[206:207], v[56:57], v[54:55]
	v_mov_b32_e32 v56, v1
	v_mov_b32_e32 v57, v3
	v_mov_b32_e32 v54, v0
	v_mov_b32_e32 v55, v2
	v_pk_mul_f32 v[56:57], v[56:57], v[56:57]
	s_nop 0
	v_pk_fma_f32 v[54:55], v[54:55], v[54:55], v[56:57]
	s_nop 0
	v_pk_add_f32 v[58:59], v[54:55], v[54:55] op_sel_hi:[0,1]
	v_cvt_pk_bf16_f32 v54, v0, v1
	v_cvt_pk_bf16_f32 v55, v2, v3
	global_store_dwordx2 v[34:35], v[54:55], off offset:512
	v_pk_fma_f32 v[50:51], v[208:209], v[50:51], v[52:53]
	v_pk_fma_f32 v[44:45], v[210:211], v[48:49], v[44:45]
	v_cvt_pk_bf16_f32 v52, v50, v51
	v_cvt_pk_bf16_f32 v53, v44, v45
	global_store_dwordx2 v[34:35], v[52:53], off offset:1024
	v_mul_f32_e32 v48, v50, v50
	v_pk_fma_f32 v[48:49], v[50:51], v[50:51], v[48:49] op_sel_hi:[1,1,0]
	v_pk_fma_f32 v[40:41], v[212:213], v[40:41], v[42:43]
	v_mul_f32_e32 v48, v44, v44
	v_pk_fma_f32 v[36:37], v[214:215], v[38:39], v[36:37]
	v_pk_fma_f32 v[56:57], v[44:45], v[44:45], v[48:49] op_sel_hi:[1,1,0]
	v_pk_mul_f32 v[38:39], v[40:41], v[40:41]
	v_pk_mul_f32 v[42:43], v[36:37], v[36:37]
	v_mov_b32_e32 v48, v38
	v_mov_b32_e32 v56, v39
	v_mov_b32_e32 v64, v42
	v_mov_b32_e32 v58, v43
	v_pk_add_f32 v[38:39], v[48:49], v[56:57]
	v_pk_add_f32 v[42:43], v[64:65], v[58:59]
	s_nop 0
	v_pk_add_f32 v[38:39], v[38:39], v[42:43]
	s_nop 0
	v_add_f32_e32 v5, v38, v39
	v_cvt_pk_bf16_f32 v38, v40, v41
	v_cvt_pk_bf16_f32 v39, v36, v37
	global_store_dwordx2 v[34:35], v[38:39], off offset:1536
	v_add_f32_dpp v5, v5, v5 quad_perm:[1,0,3,2] row_mask:0xf bank_mask:0xf bound_ctrl:1
	v_lshl_add_u64 v[38:39], v[8:9], 0, v[140:141]
	v_lshl_add_u64 v[8:9], v[8:9], 0, s[82:83]
	v_add_f32_dpp v5, v5, v5 quad_perm:[2,3,0,1] row_mask:0xf bank_mask:0xf bound_ctrl:1
	s_nop 1
	v_add_f32_dpp v5, v5, v5 row_half_mirror row_mask:0xf bank_mask:0xf bound_ctrl:1
	s_nop 1
	v_add_f32_dpp v5, v5, v5 row_mirror row_mask:0xf bank_mask:0xf bound_ctrl:1
	s_nop 0
	v_readlane_b32 s0, v5, 16
	v_readlane_b32 s10, v5, 48
	v_readlane_b32 s4, v5, 0
	v_readlane_b32 s5, v5, 32
	v_mov_b32_e32 v34, s0
	v_mov_b32_e32 v35, s10
	v_pk_add_f32 v[34:35], s[4:5], v[34:35]
	s_mov_b32 s0, 0x5100000
	v_add_f32_e32 v5, v34, v35
	v_fmamk_f32 v5, v5, 0x3a800000, v177
	v_cmp_gt_f32_e32 vcc, s65, v5
	v_mul_f32_e32 v34, 0x4b800000, v5
	s_nop 0
	v_cndmask_b32_e32 v5, v5, v34, vcc
	v_rsq_f32_e32 v5, v5
	s_nop 0
	v_mul_f32_e32 v34, 0x45800000, v5
	v_cndmask_b32_e32 v34, v5, v34, vcc
	v_pk_mul_f32 v[42:43], v[66:67], v[34:35] op_sel_hi:[1,0]
	v_add_co_u32_e32 v38, vcc, s0, v38
	v_pk_mul_f32 v[0:1], v[0:1], v[34:35] op_sel_hi:[1,0]
	s_nop 0
	v_addc_co_u32_e32 v39, vcc, 0, v39, vcc
	v_pk_mul_f32 v[2:3], v[2:3], v[34:35] op_sel_hi:[1,0]
	v_pk_mul_f32 v[40:41], v[40:41], v[34:35] op_sel_hi:[1,0]
	v_pk_mul_f32 v[42:43], v[216:217], v[42:43]
	v_pk_mul_f32 v[46:47], v[62:63], v[34:35] op_sel_hi:[1,0]
	v_cvt_pk_bf16_f32 v42, v42, v43
	v_pk_mul_f32 v[46:47], v[218:219], v[46:47]
	s_nop 0
	v_cvt_pk_bf16_f32 v43, v46, v47
	global_store_dwordx2 v[38:39], v[42:43], off
	v_pk_mul_f32 v[42:43], v[50:51], v[34:35] op_sel_hi:[1,0]
	v_pk_mul_f32 v[0:1], v[220:221], v[0:1]
	v_pk_mul_f32 v[2:3], v[222:223], v[2:3]
	v_cvt_pk_bf16_f32 v0, v0, v1
	v_cvt_pk_bf16_f32 v1, v2, v3
	global_store_dwordx2 v[38:39], v[0:1], off offset:512
	v_pk_mul_f32 v[0:1], v[224:225], v[42:43]
	v_pk_mul_f32 v[42:43], v[44:45], v[34:35] op_sel_hi:[1,0]
	v_cvt_pk_bf16_f32 v0, v0, v1
	v_pk_mul_f32 v[2:3], v[226:227], v[42:43]
	v_pk_mul_f32 v[34:35], v[36:37], v[34:35] op_sel_hi:[1,0]
	v_cvt_pk_bf16_f32 v1, v2, v3
	global_store_dwordx2 v[38:39], v[0:1], off offset:1024
	v_mov_b64_e32 v[36:37], v[22:23]
	v_mov_b64_e32 v[42:43], v[30:31]
	v_mov_b64_e32 v[44:45], v[32:33]
	v_pk_mul_f32 v[0:1], v[228:229], v[40:41]
	v_pk_mul_f32 v[2:3], v[230:231], v[34:35]
	v_cvt_pk_bf16_f32 v0, v0, v1
	v_cvt_pk_bf16_f32 v1, v2, v3
	global_store_dwordx2 v[38:39], v[0:1], off offset:1536
	v_mov_b64_e32 v[0:1], v[18:19]
	v_mov_b64_e32 v[34:35], v[20:21]
	v_mov_b64_e32 v[40:41], v[24:25]
	v_mov_b64_e32 v[2:3], v[26:27]
	v_mov_b64_e32 v[38:39], v[28:29]
	s_andn2_b64 exec, exec, s[6:7]
	s_cbranch_execz .LBB0_1157

; __device__ __forceinline__ int ltid() { int t = threadIdx.x; asm volatile("" : "+v"(t)); return t; }
; template <bool SRC_F32, bool DST_F32, bool HAS_H>
; __device__ __forceinline__ void phase_rowpass(const void* xp, const void* xs, const bf16* Y, float coef, const float* gpost, const float* gpre, void* xdst, bf16* H) {
;     const int tid = ltid(), lane = tid & 63, wave = tid >> 6;
;     const int gw = blockIdx.x * NWAVES + wave, NGW = gridDim.x * NWAVES;
;     f32x4 y[4], x[4], nxf[4]; u32x2 ny[4], nxb[4];
;     ...
;     if (gw < MR) RP_LOAD(gw);
;     for (int m = gw; m < MR; m += NGW) {
; #pragma unroll
;         for (int j = 0; j < 4; ++j) { y[j] = (f32x4){bflo(ny[j].x), bfhi(ny[j].x), bflo(ny[j].y), bfhi(ny[j].y)};
;             x[j] = SRC_F32 ? nxf[j] : (f32x4){bflo(nxb[j].x), bfhi(nxb[j].x), bflo(nxb[j].y), bfhi(nxb[j].y)}; }
;         if (m + NGW < MR) RP_LOAD(m + NGW);
.LBB0_1368:
	s_or_b64 exec, exec, s[4:5]
	v_readlane_b32 s4, v253, 2
	v_readlane_b32 s5, v253, 3
	s_waitcnt lgkmcnt(0)
	s_barrier
	s_load_dwordx4 s[8:11], s[4:5], 0xe0
	s_nop 0
	s_load_dwordx2 s[4:5], s[4:5], 0x40
	v_readlane_b32 s6, v255, 2
	v_readlane_b32 s7, v255, 3
	s_waitcnt lgkmcnt(0)
	s_add_u32 s12, s10, 0x142e0000
	s_addc_u32 s13, s11, 0
	s_add_u32 s14, s4, s6
	s_addc_u32 s15, s5, s7
	v_readlane_b32 s6, v254, 58
	v_readlane_b32 s7, v254, 59
	s_mov_b64 s[4:5], -1
	s_and_b64 vcc, exec, s[6:7]
	s_cbranch_vccz .LBB0_1375
	v_mov_b32_e32 v0, v172
	v_readlane_b32 s0, v253, 6
	v_ashrrev_i32_e32 v6, 6, v0
	s_nop 0
	v_add_u32_e32 v4, s0, v6
	v_cmp_gt_i32_e32 vcc, s93, v4
	s_and_saveexec_b64 s[6:7], vcc
	s_cbranch_execz .LBB0_1374
	v_ashrrev_i32_e32 v5, 31, v4
	v_and_b32_e32 v12, 63, v0
	v_lshlrev_b64 v[8:9], 11, v[4:5]
	v_lshl_add_u64 v[0:1], s[12:13], 0, v[8:9]
	v_lshlrev_b32_e32 v140, 3, v12
	v_lshl_add_u64 v[8:9], s[10:11], 0, v[8:9]
	v_lshl_add_u64 v[8:9], v[8:9], 0, v[140:141]
	s_mov_b64 s[4:5], 0x18360000
	v_lshl_add_u64 v[0:1], v[0:1], 0, v[140:141]
	v_lshl_add_u64 v[10:11], v[8:9], 0, s[4:5]
	v_add_co_u32_e32 v8, vcc, 0x18360000, v8
	global_load_dwordx2 v[30:31], v[0:1], off
	global_load_dwordx2 v[28:29], v[0:1], off offset:512
	global_load_dwordx2 v[2:3], v[0:1], off offset:1024
	s_nop 0
	global_load_dwordx2 v[0:1], v[0:1], off offset:1536
	v_addc_co_u32_e32 v9, vcc, 0, v9, vcc
	global_load_dwordx2 v[32:33], v[10:11], off offset:1024
	global_load_dwordx2 v[34:35], v[10:11], off offset:1536
	global_load_dwordx2 v[38:39], v[8:9], off
	global_load_dwordx2 v[36:37], v[10:11], off offset:512
	v_readlane_b32 s0, v254, 21
	v_mov_b32_e32 v7, v141
	v_lshlrev_b64 v[10:11], 12, v[4:5]
	v_add_u32_e32 v8, s0, v6
	v_ashrrev_i32_e32 v9, 31, v8
	v_lshlrev_b32_e32 v6, 4, v12
	v_lshlrev_b64 v[14:15], 11, v[8:9]
	v_lshl_add_u64 v[12:13], s[14:15], 0, v[6:7]
	v_or_b32_e32 v10, v10, v6
	s_mov_b64 s[4:5], 0x5000
	v_or_b32_e32 v14, v14, v140
	s_mov_b64 s[16:17], 0
	v_lshl_add_u64 v[6:7], v[12:13], 0, s[4:5]
	v_lshl_add_u64 v[8:9], s[8:9], 0, v[10:11]
	v_lshl_add_u64 v[10:11], s[12:13], 0, v[14:15]
	s_waitcnt vmcnt(7)
	v_mov_b64_e32 v[18:19], v[30:31]
	s_waitcnt vmcnt(6)
	v_mov_b64_e32 v[16:17], v[28:29]
	s_waitcnt vmcnt(5)
	v_mov_b64_e32 v[14:15], v[2:3]
	s_waitcnt vmcnt(4)
	v_mov_b64_e32 v[12:13], v[0:1]
	s_waitcnt vmcnt(3)
	v_mov_b64_e32 v[20:21], v[32:33]
	s_waitcnt vmcnt(2)
	v_mov_b64_e32 v[26:27], v[34:35]
	s_waitcnt vmcnt(0)
	v_mov_b64_e32 v[22:23], v[36:37]
	v_mov_b64_e32 v[24:25], v[38:39]
	global_load_dwordx4 v[200:203], v[6:7], off
	global_load_dwordx4 v[204:207], v[6:7], off offset:1024
	global_load_dwordx4 v[208:211], v[6:7], off offset:2048
	global_load_dwordx4 v[212:215], v[6:7], off offset:3072
	s_waitcnt vmcnt(0)
	s_branch .LBB0_1372
; __device__ __forceinline__ unsigned pk2(float lo, float hi) { f32x2_t v = {lo, hi}; bf16x2_t b = __builtin_convertvector(v, bf16x2_t); return __builtin_bit_cast(unsigned, b); }
; template <bool SRC_F32, bool DST_F32, bool HAS_H>
; __device__ __forceinline__ void phase_rowpass(const void* xp, const void* xs, const bf16* Y, float coef, const float* gpost, const float* gpre, void* xdst, bf16* H) {
;     ...
;     for (int m = gw; m < MR; m += NGW) {
; #pragma unroll
;         for (int j = 0; j < 4; ++j) { y[j] = (f32x4){bflo(ny[j].x), bfhi(ny[j].x), bflo(ny[j].y), bfhi(ny[j].y)};
;             x[j] = SRC_F32 ? nxf[j] : (f32x4){bflo(nxb[j].x), bfhi(nxb[j].x), bflo(nxb[j].y), bfhi(nxb[j].y)}; }
;         if (m + NGW < MR) RP_LOAD(m + NGW);
;         float s = 0.f;
; #pragma unroll
;         for (int j = 0; j < 4; ++j) s += (y[j].x * y[j].x + y[j].y * y[j].y) + (y[j].z * y[j].z + y[j].w * y[j].w);
;         const float rstd = rsqrtf(wave_sum(s) * (1.f / D) + RMS_EPS) * coef;
;         float s2 = 0.f;
; #pragma unroll
;         for (int j = 0; j < 4; ++j) { const f32x4 gg = *((const f32x4*)gpost + lane + 64 * j);
;             x[j].x += y[j].x * rstd * gg.x; x[j].y += y[j].y * rstd * gg.y; x[j].z += y[j].z * rstd * gg.z; x[j].w += y[j].w * rstd * gg.w;
;             s2 += (x[j].x * x[j].x + x[j].y * x[j].y) + (x[j].z * x[j].z + x[j].w * x[j].w);
;             if (DST_F32) *((f32x4*)((float*)xdst + (size_t)m * D) + lane + 64 * j) = x[j];
;             else { u32x2 o; o.x = pk2(x[j].x, x[j].y); o.y = pk2(x[j].z, x[j].w); *((u32x2*)((bf16*)xdst + (size_t)m * D) + lane + 64 * j) = o; } }
.LBB0_1371:
	s_or_b64 exec, exec, s[4:5]
	v_and_b32_e32 v59, 0xffff0000, v30
	v_and_b32_e32 v57, 0xffff0000, v31
	v_lshlrev_b32_e32 v58, 16, v30
	v_lshlrev_b32_e32 v60, 16, v38
	v_and_b32_e32 v61, 0xffff0000, v38
	v_lshlrev_b32_e32 v56, 16, v31
	v_lshlrev_b32_e32 v54, 16, v39
	v_and_b32_e32 v55, 0xffff0000, v39
	v_lshlrev_b32_e32 v38, 16, v3
	v_and_b32_e32 v39, 0xffff0000, v3
	v_lshlrev_b32_e32 v40, 16, v2
	v_and_b32_e32 v41, 0xffff0000, v2
	v_mov_b32_e32 v2, v59
	v_mov_b32_e32 v3, v57
	v_lshlrev_b32_e32 v49, 16, v29
	v_lshlrev_b32_e32 v48, 16, v28
	v_and_b32_e32 v47, 0xffff0000, v29
	v_and_b32_e32 v46, 0xffff0000, v28
	v_lshlrev_b32_e32 v52, 16, v36
	v_and_b32_e32 v53, 0xffff0000, v36
	v_lshlrev_b32_e32 v44, 16, v37
	v_and_b32_e32 v45, 0xffff0000, v37
	v_lshlrev_b32_e32 v42, 16, v32
	v_and_b32_e32 v43, 0xffff0000, v32
	v_lshlrev_b32_e32 v36, 16, v33
	v_and_b32_e32 v37, 0xffff0000, v33
	v_lshlrev_b32_e32 v28, 16, v0
	v_and_b32_e32 v29, 0xffff0000, v0
	v_lshlrev_b32_e32 v32, 16, v1
	v_and_b32_e32 v33, 0xffff0000, v1
	v_mov_b32_e32 v0, v58
	v_mov_b32_e32 v1, v56
	v_pk_mul_f32 v[2:3], v[2:3], v[2:3]
	v_pk_mul_f32 v[62:63], v[28:29], v[28:29]
	v_pk_fma_f32 v[0:1], v[0:1], v[0:1], v[2:3]
	v_pk_mul_f32 v[2:3], v[46:47], v[46:47]
	v_pk_add_f32 v[0:1], v[0:1], v[0:1] op_sel_hi:[0,1]
	v_mul_f32_e32 v0, v38, v38
	v_pk_fma_f32 v[2:3], v[48:49], v[48:49], v[2:3]
	v_pk_fma_f32 v[50:51], v[38:39], v[38:39], v[0:1] op_sel_hi:[1,1,0]
	v_mul_f32_e32 v0, v40, v40
	v_pk_add_f32 v[2:3], v[2:3], v[2:3] op_sel_hi:[0,1]
	v_pk_mul_f32 v[64:65], v[32:33], v[32:33]
	v_pk_fma_f32 v[66:67], v[40:41], v[40:41], v[0:1] op_sel_hi:[1,1,0]
	v_mov_b32_e32 v50, v63
	v_mov_b32_e32 v66, v62
	v_mov_b32_e32 v2, v64
	v_mov_b32_e32 v0, v65
	v_pk_add_f32 v[50:51], v[66:67], v[50:51]
	v_pk_add_f32 v[0:1], v[2:3], v[0:1]
	v_lshlrev_b32_e32 v30, 16, v34
	v_pk_add_f32 v[0:1], v[50:51], v[0:1]
	v_and_b32_e32 v31, 0xffff0000, v34
	v_add_f32_e32 v0, v0, v1
	v_lshlrev_b32_e32 v34, 16, v35
	v_and_b32_e32 v35, 0xffff0000, v35
	v_add_f32_dpp v0, v0, v0 quad_perm:[1,0,3,2] row_mask:0xf bank_mask:0xf bound_ctrl:1
	v_lshl_add_u64 v[10:11], v[10:11], 0, s[82:83]
	s_nop 0
	v_add_f32_dpp v0, v0, v0 quad_perm:[2,3,0,1] row_mask:0xf bank_mask:0xf bound_ctrl:1
	s_nop 1
	v_add_f32_dpp v0, v0, v0 row_half_mirror row_mask:0xf bank_mask:0xf bound_ctrl:1
	s_nop 1
	v_add_f32_dpp v0, v0, v0 row_mirror row_mask:0xf bank_mask:0xf bound_ctrl:1
	s_nop 0
	v_readlane_b32 s0, v0, 16
	v_readlane_b32 s18, v0, 48
	v_readlane_b32 s4, v0, 0
	v_readlane_b32 s5, v0, 32
	v_mov_b32_e32 v0, s0
	v_mov_b32_e32 v1, s18
	v_pk_add_f32 v[0:1], s[4:5], v[0:1]
	v_readlane_b32 s4, v254, 41
	v_add_f32_e32 v0, v0, v1
	v_fmamk_f32 v0, v0, 0x3a800000, v177
	v_cmp_gt_f32_e32 vcc, s65, v0
	v_mul_f32_e32 v1, 0x4b800000, v0
	v_readlane_b32 s5, v254, 42
	v_cndmask_b32_e32 v0, v0, v1, vcc
	v_rsq_f32_e32 v0, v0
	s_nop 0
	v_mul_f32_e32 v1, 0x45800000, v0
	v_cndmask_b32_e32 v0, v0, v1, vcc
	v_mul_f32_e32 v50, 0.5, v0
	v_pk_mul_f32 v[58:59], v[50:51], v[58:59] op_sel_hi:[0,1]
	v_pk_mul_f32 v[56:57], v[50:51], v[56:57] op_sel_hi:[0,1]
	v_pk_mul_f32 v[40:41], v[50:51], v[40:41] op_sel_hi:[0,1]
	v_pk_mul_f32 v[38:39], v[50:51], v[38:39] op_sel_hi:[0,1]
	v_pk_mul_f32 v[28:29], v[50:51], v[28:29] op_sel_hi:[0,1]
	s_waitcnt vmcnt(0)
	v_pk_fma_f32 v[0:1], v[200:201], v[58:59], v[60:61]
	v_pk_fma_f32 v[2:3], v[202:203], v[56:57], v[54:55]
	global_store_dwordx4 v[8:9], v[0:3], off
	s_nop 1
	v_mov_b32_e32 v54, v48
	v_mov_b32_e32 v55, v46
	v_mov_b32_e32 v46, v49
	v_pk_mul_f32 v[54:55], v[50:51], v[54:55] op_sel_hi:[0,1]
	v_pk_mul_f32 v[46:47], v[50:51], v[46:47] op_sel_hi:[0,1]
	v_pk_fma_f32 v[0:1], v[204:205], v[54:55], v[52:53]
	v_pk_fma_f32 v[2:3], v[206:207], v[46:47], v[44:45]
	global_store_dwordx4 v[8:9], v[0:3], off offset:1024
	s_nop 1
	v_pk_fma_f32 v[0:1], v[208:209], v[40:41], v[42:43]
	v_pk_fma_f32 v[2:3], v[210:211], v[38:39], v[36:37]
	global_store_dwordx4 v[8:9], v[0:3], off offset:2048
	s_nop 1
	v_mov_b64_e32 v[36:37], v[22:23]
	v_mov_b64_e32 v[38:39], v[24:25]
	v_pk_fma_f32 v[0:1], v[212:213], v[28:29], v[30:31]
	v_pk_mul_f32 v[28:29], v[50:51], v[32:33] op_sel_hi:[0,1]
	v_pk_fma_f32 v[2:3], v[214:215], v[28:29], v[34:35]
	global_store_dwordx4 v[8:9], v[0:3], off offset:3072
	s_nop 1
	v_lshl_add_u64 v[8:9], v[8:9], 0, s[4:5]
	v_mov_b64_e32 v[28:29], v[16:17]
	v_mov_b64_e32 v[0:1], v[12:13]
	v_mov_b64_e32 v[2:3], v[14:15]
	v_mov_b64_e32 v[30:31], v[18:19]
	v_mov_b64_e32 v[34:35], v[26:27]
	v_mov_b64_e32 v[32:33], v[20:21]
	s_andn2_b64 exec, exec, s[16:17]
	s_cbranch_execz .LBB0_1374

; __device__ __forceinline__ int ltid() { int t = threadIdx.x; asm volatile("" : "+v"(t)); return t; }
; template <bool SRC_F32, bool DST_F32, bool HAS_H>
; __device__ __forceinline__ void phase_rowpass(const void* xp, const void* xs, const bf16* Y, float coef, const float* gpost, const float* gpre, void* xdst, bf16* H) {
;     const int tid = ltid(), lane = tid & 63, wave = tid >> 6;
;     const int gw = blockIdx.x * NWAVES + wave, NGW = gridDim.x * NWAVES;
;     f32x4 y[4], x[4], nxf[4]; u32x2 ny[4], nxb[4];
;     ...
;     if (gw < MR) RP_LOAD(gw);
;     for (int m = gw; m < MR; m += NGW) {
; #pragma unroll
;         for (int j = 0; j < 4; ++j) { y[j] = (f32x4){bflo(ny[j].x), bfhi(ny[j].x), bflo(ny[j].y), bfhi(ny[j].y)};
;             x[j] = SRC_F32 ? nxf[j] : (f32x4){bflo(nxb[j].x), bfhi(nxb[j].x), bflo(nxb[j].y), bfhi(nxb[j].y)}; }
;         if (m + NGW < MR) RP_LOAD(m + NGW);
;         float s = 0.f;
; #pragma unroll
;         for (int j = 0; j < 4; ++j) s += (y[j].x * y[j].x + y[j].y * y[j].y) + (y[j].z * y[j].z + y[j].w * y[j].w);
;         const float rstd = rsqrtf(wave_sum(s) * (1.f / D) + RMS_EPS) * coef;
;         float s2 = 0.f;
; #pragma unroll
;         for (int j = 0; j < 4; ++j) { const f32x4 gg = *((const f32x4*)gpost + lane + 64 * j);
;             x[j].x += y[j].x * rstd * gg.x; x[j].y += y[j].y * rstd * gg.y; x[j].z += y[j].z * rstd * gg.z; x[j].w += y[j].w * rstd * gg.w;
.LBB0_1375:
	s_andn2_b64 vcc, exec, s[4:5]
	s_cbranch_vccnz .LBB0_1382
	v_mov_b32_e32 v0, v172
	v_readlane_b32 s0, v253, 6
	v_ashrrev_i32_e32 v8, 6, v0
	s_nop 0
	v_add_u32_e32 v4, s0, v8
	v_cmp_gt_i32_e32 vcc, s93, v4
	s_and_saveexec_b64 s[6:7], vcc
	s_cbranch_execz .LBB0_1381
	v_ashrrev_i32_e32 v5, 31, v4
	v_and_b32_e32 v14, 63, v0
	v_lshlrev_b64 v[10:11], 11, v[4:5]
	v_lshl_add_u64 v[0:1], s[12:13], 0, v[10:11]
	v_lshlrev_b32_e32 v140, 3, v14
	v_lshl_add_u64 v[6:7], s[8:9], 0, v[10:11]
	v_lshl_add_u64 v[2:3], v[0:1], 0, v[140:141]
	v_lshl_add_u64 v[12:13], v[6:7], 0, v[140:141]
	global_load_dwordx2 v[40:41], v[2:3], off
	global_load_dwordx2 v[36:37], v[2:3], off offset:512
	global_load_dwordx2 v[0:1], v[2:3], off offset:1536
	global_load_dwordx2 v[34:35], v[2:3], off offset:1024
	s_nop 0
	global_load_dwordx2 v[2:3], v[12:13], off offset:1536
	global_load_dwordx2 v[38:39], v[12:13], off offset:1024
	global_load_dwordx2 v[42:43], v[12:13], off offset:512
	global_load_dwordx2 v[44:45], v[12:13], off
	v_readlane_b32 s0, v254, 21
	v_mov_b32_e32 v9, v141
	s_mov_b64 s[4:5], 0x5000
	v_add_u32_e32 v12, s0, v8
	v_lshlrev_b32_e32 v8, 4, v14
	v_ashrrev_i32_e32 v13, 31, v12
	v_lshl_add_u64 v[14:15], s[14:15], 0, v[8:9]
	v_lshl_add_u64 v[8:9], s[10:11], 0, v[10:11]
	v_lshlrev_b64 v[16:17], 11, v[12:13]
	v_lshl_add_u64 v[10:11], v[14:15], 0, s[4:5]
	s_mov_b64 s[4:5], 0x6000
	s_mov_b64 s[12:13], 0
	v_lshl_add_u64 v[12:13], v[14:15], 0, s[4:5]
	v_lshl_add_u64 v[14:15], s[10:11], 0, v[16:17]
	v_lshl_add_u64 v[16:17], s[8:9], 0, v[16:17]
	s_waitcnt vmcnt(7)
	v_mov_b64_e32 v[24:25], v[40:41]
	s_waitcnt vmcnt(6)
	v_mov_b64_e32 v[22:23], v[36:37]
	s_waitcnt vmcnt(5)
	v_mov_b64_e32 v[18:19], v[0:1]
	s_waitcnt vmcnt(4)
	v_mov_b64_e32 v[20:21], v[34:35]
	s_waitcnt vmcnt(3)
	v_mov_b64_e32 v[26:27], v[2:3]
	s_waitcnt vmcnt(2)
	v_mov_b64_e32 v[28:29], v[38:39]
	s_waitcnt vmcnt(1)
	v_mov_b64_e32 v[30:31], v[42:43]
	s_waitcnt vmcnt(0)
	v_mov_b64_e32 v[32:33], v[44:45]
	global_load_dwordx4 v[200:203], v[10:11], off
	global_load_dwordx4 v[204:207], v[10:11], off offset:1024
	global_load_dwordx4 v[208:211], v[10:11], off offset:2048
	global_load_dwordx4 v[212:215], v[10:11], off offset:3072
	global_load_dwordx4 v[216:219], v[12:13], off
	global_load_dwordx4 v[220:223], v[12:13], off offset:1024
	global_load_dwordx4 v[224:227], v[12:13], off offset:2048
	global_load_dwordx4 v[228:231], v[12:13], off offset:3072
	s_waitcnt vmcnt(0)
	s_branch .LBB0_1379
.LBB0_1378:
	s_or_b64 exec, exec, s[4:5]
	v_and_b32_e32 v67, 0xffff0000, v40
	v_and_b32_e32 v65, 0xffff0000, v41
	v_lshlrev_b32_e32 v66, 16, v40
	v_lshlrev_b32_e32 v64, 16, v41
	v_lshlrev_b32_e32 v59, 16, v37
	v_lshlrev_b32_e32 v58, 16, v36
	v_and_b32_e32 v57, 0xffff0000, v37
	v_and_b32_e32 v56, 0xffff0000, v36
	v_lshlrev_b32_e32 v60, 16, v42
	v_and_b32_e32 v61, 0xffff0000, v42
	v_lshlrev_b32_e32 v54, 16, v43
	v_and_b32_e32 v55, 0xffff0000, v43
	v_lshlrev_b32_e32 v42, 16, v2
	v_and_b32_e32 v43, 0xffff0000, v2
	v_lshlrev_b32_e32 v36, 16, v3
	v_and_b32_e32 v37, 0xffff0000, v3
	v_mov_b32_e32 v2, v67
	v_mov_b32_e32 v3, v65
	v_lshlrev_b32_e32 v68, 16, v44
	v_and_b32_e32 v69, 0xffff0000, v44
	v_lshlrev_b32_e32 v62, 16, v45
	v_and_b32_e32 v63, 0xffff0000, v45
	v_lshlrev_b32_e32 v52, 16, v38
	v_and_b32_e32 v53, 0xffff0000, v38
	v_lshlrev_b32_e32 v44, 16, v39
	v_and_b32_e32 v45, 0xffff0000, v39
	v_lshlrev_b32_e32 v40, 16, v0
	v_and_b32_e32 v41, 0xffff0000, v0
	v_lshlrev_b32_e32 v38, 16, v1
	v_and_b32_e32 v39, 0xffff0000, v1
	v_mov_b32_e32 v0, v66
	v_mov_b32_e32 v1, v64
	v_pk_mul_f32 v[2:3], v[2:3], v[2:3]
	v_lshlrev_b32_e32 v46, 16, v35
	v_pk_fma_f32 v[0:1], v[0:1], v[0:1], v[2:3]
	v_and_b32_e32 v47, 0xffff0000, v35
	v_pk_add_f32 v[0:1], v[0:1], v[0:1] op_sel_hi:[0,1]
	v_lshlrev_b32_e32 v50, 16, v34
	v_pk_mul_f32 v[2:3], v[56:57], v[56:57]
	v_mul_f32_e32 v0, v46, v46
	v_and_b32_e32 v51, 0xffff0000, v34
	v_pk_fma_f32 v[2:3], v[58:59], v[58:59], v[2:3]
	v_pk_fma_f32 v[34:35], v[46:47], v[46:47], v[0:1] op_sel_hi:[1,1,0]
	v_mul_f32_e32 v0, v50, v50
	v_pk_add_f32 v[2:3], v[2:3], v[2:3] op_sel_hi:[0,1]
	v_pk_mul_f32 v[48:49], v[40:41], v[40:41]
	v_pk_mul_f32 v[70:71], v[38:39], v[38:39]
	v_pk_fma_f32 v[72:73], v[50:51], v[50:51], v[0:1] op_sel_hi:[1,1,0]
	v_mov_b32_e32 v34, v49
	v_mov_b32_e32 v72, v48
	v_mov_b32_e32 v2, v70
	v_mov_b32_e32 v0, v71
	v_pk_add_f32 v[34:35], v[72:73], v[34:35]
	v_pk_add_f32 v[0:1], v[2:3], v[0:1]
	v_lshl_add_u64 v[14:15], v[14:15], 0, s[82:83]
	v_pk_add_f32 v[0:1], v[34:35], v[0:1]
	v_lshl_add_u64 v[34:35], v[6:7], 0, v[140:141]
	v_add_f32_e32 v0, v0, v1
	v_lshl_add_u64 v[6:7], v[6:7], 0, s[82:83]
	v_lshl_add_u64 v[16:17], v[16:17], 0, s[82:83]
	v_add_f32_dpp v0, v0, v0 quad_perm:[1,0,3,2] row_mask:0xf bank_mask:0xf bound_ctrl:1
	s_nop 1
	v_add_f32_dpp v0, v0, v0 quad_perm:[2,3,0,1] row_mask:0xf bank_mask:0xf bound_ctrl:1
	s_nop 1
	v_add_f32_dpp v0, v0, v0 row_half_mirror row_mask:0xf bank_mask:0xf bound_ctrl:1
	s_nop 1
	v_add_f32_dpp v0, v0, v0 row_mirror row_mask:0xf bank_mask:0xf bound_ctrl:1
	s_nop 0
	v_readlane_b32 s0, v0, 16
	v_readlane_b32 s8, v0, 48
	v_readlane_b32 s4, v0, 0
	v_readlane_b32 s5, v0, 32
	v_mov_b32_e32 v0, s0
	v_mov_b32_e32 v1, s8
	v_pk_add_f32 v[0:1], s[4:5], v[0:1]
	s_nop 0
	v_add_f32_e32 v0, v0, v1
	v_fmamk_f32 v0, v0, 0x3a800000, v177
	v_cmp_gt_f32_e32 vcc, s65, v0
	v_mul_f32_e32 v1, 0x4b800000, v0
	s_nop 0
	v_cndmask_b32_e32 v0, v0, v1, vcc
	v_rsq_f32_e32 v0, v0
	s_nop 0
	v_mul_f32_e32 v1, 0x45800000, v0
	v_cndmask_b32_e32 v0, v0, v1, vcc
	v_mul_f32_e32 v48, 0.5, v0
	v_pk_mul_f32 v[66:67], v[48:49], v[66:67] op_sel_hi:[0,1]
	v_pk_mul_f32 v[50:51], v[48:49], v[50:51] op_sel_hi:[0,1]
	v_pk_mul_f32 v[46:47], v[48:49], v[46:47] op_sel_hi:[0,1]
	v_pk_mul_f32 v[40:41], v[48:49], v[40:41] op_sel_hi:[0,1]
	v_pk_mul_f32 v[38:39], v[48:49], v[38:39] op_sel_hi:[0,1]
	s_waitcnt vmcnt(0)
; __device__ __forceinline__ unsigned pk2(float lo, float hi) { f32x2_t v = {lo, hi}; bf16x2_t b = __builtin_convertvector(v, bf16x2_t); return __builtin_bit_cast(unsigned, b); }
; template <bool SRC_F32, bool DST_F32, bool HAS_H>
; __device__ __forceinline__ void phase_rowpass(const void* xp, const void* xs, const bf16* Y, float coef, const float* gpost, const float* gpre, void* xdst, bf16* H) {
;     ...
;         for (int j = 0; j < 4; ++j) { const f32x4 gg = *((const f32x4*)gpost + lane + 64 * j);
;             x[j].x += y[j].x * rstd * gg.x; x[j].y += y[j].y * rstd * gg.y; x[j].z += y[j].z * rstd * gg.z; x[j].w += y[j].w * rstd * gg.w;
;             s2 += (x[j].x * x[j].x + x[j].y * x[j].y) + (x[j].z * x[j].z + x[j].w * x[j].w);
;             if (DST_F32) *((f32x4*)((float*)xdst + (size_t)m * D) + lane + 64 * j) = x[j];
;             else { u32x2 o; o.x = pk2(x[j].x, x[j].y); o.y = pk2(x[j].z, x[j].w); *((u32x2*)((bf16*)xdst + (size_t)m * D) + lane + 64 * j) = o; } }
;         if (HAS_H) {
;             const float r2 = rsqrtf(wave_sum(s2) * (1.f / D) + RMS_EPS);
; #pragma unroll
;             for (int j = 0; j < 4; ++j) { const f32x4 gg = *((const f32x4*)gpre + lane + 64 * j); u32x2 o; o.x = pk2(x[j].x * r2 * gg.x, x[j].y * r2 * gg.y); o.y = pk2(x[j].z * r2 * gg.z, x[j].w * r2 * gg.w);
;                 *((u32x2*)(H + (size_t)m * D) + lane + 64 * j) = o; }
	v_pk_fma_f32 v[66:67], v[200:201], v[66:67], v[68:69]
	v_pk_mul_f32 v[0:1], v[48:49], v[64:65] op_sel_hi:[0,1]
	v_pk_fma_f32 v[62:63], v[202:203], v[0:1], v[62:63]
	v_mov_b32_e32 v2, v67
	v_mov_b32_e32 v3, v63
	v_mov_b32_e32 v0, v66
	v_mov_b32_e32 v1, v62
	v_pk_mul_f32 v[2:3], v[2:3], v[2:3]
	v_mov_b32_e32 v68, v58
	v_pk_fma_f32 v[0:1], v[0:1], v[0:1], v[2:3]
	v_mov_b32_e32 v69, v56
	v_pk_add_f32 v[64:65], v[0:1], v[0:1] op_sel_hi:[0,1]
	v_cvt_pk_bf16_f32 v0, v66, v67
	v_cvt_pk_bf16_f32 v1, v62, v63
	global_store_dwordx2 v[34:35], v[0:1], off
	v_mov_b32_e32 v56, v59
	v_pk_mul_f32 v[68:69], v[48:49], v[68:69] op_sel_hi:[0,1]
	v_pk_mul_f32 v[56:57], v[48:49], v[56:57] op_sel_hi:[0,1]
	v_pk_fma_f32 v[0:1], v[204:205], v[68:69], v[60:61]
	v_pk_fma_f32 v[2:3], v[206:207], v[56:57], v[54:55]
	v_mov_b32_e32 v56, v1
	v_mov_b32_e32 v57, v3
	v_mov_b32_e32 v54, v0
	v_mov_b32_e32 v55, v2
	v_pk_mul_f32 v[56:57], v[56:57], v[56:57]
	s_nop 0
	v_pk_fma_f32 v[54:55], v[54:55], v[54:55], v[56:57]
	s_nop 0
	v_pk_add_f32 v[58:59], v[54:55], v[54:55] op_sel_hi:[0,1]
	v_cvt_pk_bf16_f32 v54, v0, v1
	v_cvt_pk_bf16_f32 v55, v2, v3
	global_store_dwordx2 v[34:35], v[54:55], off offset:512
	v_pk_fma_f32 v[50:51], v[208:209], v[50:51], v[52:53]
	v_pk_fma_f32 v[44:45], v[210:211], v[46:47], v[44:45]
	v_cvt_pk_bf16_f32 v52, v50, v51
	v_cvt_pk_bf16_f32 v53, v44, v45
	global_store_dwordx2 v[34:35], v[52:53], off offset:1024
	v_mul_f32_e32 v46, v50, v50
	v_pk_fma_f32 v[46:47], v[50:51], v[50:51], v[46:47] op_sel_hi:[1,1,0]
	v_pk_fma_f32 v[40:41], v[212:213], v[40:41], v[42:43]
	v_mul_f32_e32 v46, v44, v44
	v_pk_fma_f32 v[36:37], v[214:215], v[38:39], v[36:37]
	v_pk_fma_f32 v[56:57], v[44:45], v[44:45], v[46:47] op_sel_hi:[1,1,0]
	v_pk_mul_f32 v[38:39], v[40:41], v[40:41]
	v_pk_mul_f32 v[42:43], v[36:37], v[36:37]
	v_mov_b32_e32 v46, v38
	v_mov_b32_e32 v56, v39
	v_mov_b32_e32 v64, v42
	v_mov_b32_e32 v58, v43
	v_pk_add_f32 v[38:39], v[46:47], v[56:57]
	v_pk_add_f32 v[42:43], v[64:65], v[58:59]
	s_nop 0
	v_pk_add_f32 v[38:39], v[38:39], v[42:43]
	s_nop 0
	v_add_f32_e32 v5, v38, v39
	v_cvt_pk_bf16_f32 v38, v40, v41
	v_cvt_pk_bf16_f32 v39, v36, v37
	global_store_dwordx2 v[34:35], v[38:39], off offset:1536
	v_add_f32_dpp v5, v5, v5 quad_perm:[1,0,3,2] row_mask:0xf bank_mask:0xf bound_ctrl:1
	v_lshl_add_u64 v[38:39], v[8:9], 0, v[140:141]
	v_lshl_add_u64 v[8:9], v[8:9], 0, s[82:83]
	v_add_f32_dpp v5, v5, v5 quad_perm:[2,3,0,1] row_mask:0xf bank_mask:0xf bound_ctrl:1
	s_nop 1
	v_add_f32_dpp v5, v5, v5 row_half_mirror row_mask:0xf bank_mask:0xf bound_ctrl:1
	s_nop 1
	v_add_f32_dpp v5, v5, v5 row_mirror row_mask:0xf bank_mask:0xf bound_ctrl:1
	s_nop 0
	v_readlane_b32 s0, v5, 16
	v_readlane_b32 s8, v5, 48
	v_readlane_b32 s4, v5, 0
	v_readlane_b32 s5, v5, 32
	v_mov_b32_e32 v34, s0
	v_mov_b32_e32 v35, s8
	v_pk_add_f32 v[34:35], s[4:5], v[34:35]
	s_mov_b32 s0, 0x5100000
	v_add_f32_e32 v5, v34, v35
	v_fmamk_f32 v5, v5, 0x3a800000, v177
	v_cmp_gt_f32_e32 vcc, s65, v5
	v_mul_f32_e32 v34, 0x4b800000, v5
	s_nop 0
	v_cndmask_b32_e32 v5, v5, v34, vcc
	v_rsq_f32_e32 v5, v5
	s_nop 0
	v_mul_f32_e32 v34, 0x45800000, v5
	v_cndmask_b32_e32 v34, v5, v34, vcc
	v_pk_mul_f32 v[42:43], v[66:67], v[34:35] op_sel_hi:[1,0]
	v_add_co_u32_e32 v38, vcc, s0, v38
	v_pk_mul_f32 v[0:1], v[0:1], v[34:35] op_sel_hi:[1,0]
	s_nop 0
	v_addc_co_u32_e32 v39, vcc, 0, v39, vcc
	v_pk_mul_f32 v[2:3], v[2:3], v[34:35] op_sel_hi:[1,0]
	v_pk_mul_f32 v[40:41], v[40:41], v[34:35] op_sel_hi:[1,0]
	v_pk_mul_f32 v[42:43], v[216:217], v[42:43]
	v_pk_mul_f32 v[46:47], v[62:63], v[34:35] op_sel_hi:[1,0]
	v_cvt_pk_bf16_f32 v42, v42, v43
	v_pk_mul_f32 v[46:47], v[218:219], v[46:47]
	s_nop 0
	v_cvt_pk_bf16_f32 v43, v46, v47
	global_store_dwordx2 v[38:39], v[42:43], off
	v_pk_mul_f32 v[42:43], v[50:51], v[34:35] op_sel_hi:[1,0]
	v_pk_mul_f32 v[0:1], v[220:221], v[0:1]
	v_pk_mul_f32 v[2:3], v[222:223], v[2:3]
	v_cvt_pk_bf16_f32 v0, v0, v1
	v_cvt_pk_bf16_f32 v1, v2, v3
	global_store_dwordx2 v[38:39], v[0:1], off offset:512
	v_pk_mul_f32 v[0:1], v[224:225], v[42:43]
	v_pk_mul_f32 v[42:43], v[44:45], v[34:35] op_sel_hi:[1,0]
	v_cvt_pk_bf16_f32 v0, v0, v1
	v_pk_mul_f32 v[2:3], v[226:227], v[42:43]
	v_pk_mul_f32 v[34:35], v[36:37], v[34:35] op_sel_hi:[1,0]
	v_cvt_pk_bf16_f32 v1, v2, v3
	global_store_dwordx2 v[38:39], v[0:1], off offset:1024
	v_mov_b64_e32 v[36:37], v[22:23]
	v_mov_b64_e32 v[42:43], v[30:31]
	v_mov_b64_e32 v[44:45], v[32:33]
	v_pk_mul_f32 v[0:1], v[228:229], v[40:41]
	v_pk_mul_f32 v[2:3], v[230:231], v[34:35]
	v_cvt_pk_bf16_f32 v0, v0, v1
	v_cvt_pk_bf16_f32 v1, v2, v3
	global_store_dwordx2 v[38:39], v[0:1], off offset:1536
	v_mov_b64_e32 v[0:1], v[18:19]
	v_mov_b64_e32 v[34:35], v[20:21]
	v_mov_b64_e32 v[40:41], v[24:25]
	v_mov_b64_e32 v[2:3], v[26:27]
	v_mov_b64_e32 v[38:39], v[28:29]
	s_andn2_b64 exec, exec, s[12:13]
	s_cbranch_execz .LBB0_1381
